# first K-loop iteration of every GEMM peeled with SrcC=0 on each accumulator's first MFMA; the 127-instruction accumulator zeroing before every unit removed (9 blocks)
# speedup vs baseline: 1.0098x; 1.0008x over previous
.LBB0_206:
	s_ashr_i32 s27, s26, 31
	s_lshl_b64 s[30:31], s[26:27], 18
	s_add_u32 s30, s41, s30
	s_addc_u32 s31, s42, s31
	s_and_b64 s[0:1], s[0:1], exec
	s_cselect_b32 s25, s31, s39
	s_cselect_b32 s27, s30, s38
	s_add_u32 s0, s38, 0x20080
	s_addc_u32 s1, s39, 0
	s_add_u32 s60, s36, 0x100
	v_mov_b32_e32 v2, 0
	s_addc_u32 s61, s37, 0
	s_mov_b32 s62, -2
	s_nop 0
	ds_read_b128 v[156:159], v152
	ds_read_b128 v[160:163], v152 offset:1024
	ds_read_b128 v[164:167], v152 offset:2048
	ds_read_b128 v[168:171], v152 offset:3072
	ds_read_b128 v[172:175], v153
	ds_read_b128 v[176:179], v153 offset:1024
	ds_read_b128 v[180:183], v153 offset:2048
	ds_read_b128 v[184:187], v153 offset:3072
	s_add_u32 s36, s0, 0xfffe0080
	s_addc_u32 s37, s1, -1
	s_cmp_eq_u32 s62, 4
	s_cselect_b32 s39, s25, s37
	s_cselect_b32 s38, s27, s36
	s_cselect_b32 s37, s29, s61
	s_cselect_b32 s36, s28, s60
	v_lshl_add_u64 v[146:147], s[0:1], 0, v[138:139]
	s_add_i32 m0, s35, 0xc000
	ds_read_b128 v[188:191], v154
	ds_read_b128 v[192:195], v154 offset:1024
	ds_read_b128 v[196:199], v154 offset:2048
	ds_read_b128 v[200:203], v154 offset:3072
	ds_read_b128 v[204:207], v154 offset:4096
	ds_read_b128 v[208:211], v154 offset:5120
	ds_read_b128 v[212:215], v154 offset:6144
	ds_read_b128 v[216:219], v154 offset:7168
	global_load_lds_dwordx4 v[146:147], off
	v_lshl_add_u64 v[146:147], s[0:1], 0, v[140:141]
	s_add_i32 m0, s35, 0xe000
	s_nop 0
	global_load_lds_dwordx4 v[146:147], off
	s_waitcnt vmcnt(8)
	s_waitcnt lgkmcnt(0)
	s_barrier
	s_setprio 1
	s_waitcnt lgkmcnt(0)
	v_mfma_f32_16x16x32_bf16 v[126:129], v[156:159], v[188:191], 0
	v_mfma_f32_16x16x32_bf16 v[122:125], v[164:167], v[188:191], 0
	v_mfma_f32_16x16x32_bf16 v[118:121], v[156:159], v[196:199], 0
	v_mfma_f32_16x16x32_bf16 v[110:113], v[164:167], v[196:199], 0
	v_mfma_f32_16x16x32_bf16 v[102:105], v[156:159], v[204:207], 0
	v_mfma_f32_16x16x32_bf16 v[94:97], v[164:167], v[204:207], 0
	v_mfma_f32_16x16x32_bf16 v[86:89], v[156:159], v[212:215], 0
	v_mfma_f32_16x16x32_bf16 v[78:81], v[164:167], v[212:215], 0
	v_mfma_f32_16x16x32_bf16 v[126:129], v[160:163], v[192:195], v[126:129]
	v_mfma_f32_16x16x32_bf16 v[122:125], v[168:171], v[192:195], v[122:125]
	v_mfma_f32_16x16x32_bf16 v[118:121], v[160:163], v[200:203], v[118:121]
	v_mfma_f32_16x16x32_bf16 v[110:113], v[168:171], v[200:203], v[110:113]
	v_mfma_f32_16x16x32_bf16 v[102:105], v[160:163], v[208:211], v[102:105]
	v_mfma_f32_16x16x32_bf16 v[94:97], v[168:171], v[208:211], v[94:97]
	v_mfma_f32_16x16x32_bf16 v[86:89], v[160:163], v[216:219], v[86:89]
	v_mfma_f32_16x16x32_bf16 v[78:81], v[168:171], v[216:219], v[78:81]
	s_setprio 0
	s_setprio 1
	v_mfma_f32_16x16x32_bf16 v[114:117], v[172:175], v[188:191], 0
	v_mfma_f32_16x16x32_bf16 v[106:109], v[180:183], v[188:191], 0
	v_mfma_f32_16x16x32_bf16 v[98:101], v[172:175], v[196:199], 0
	v_mfma_f32_16x16x32_bf16 v[90:93], v[180:183], v[196:199], 0
	v_mfma_f32_16x16x32_bf16 v[82:85], v[172:175], v[204:207], 0
	v_mfma_f32_16x16x32_bf16 v[74:77], v[180:183], v[204:207], 0
	v_mfma_f32_16x16x32_bf16 v[70:73], v[172:175], v[212:215], 0
	v_mfma_f32_16x16x32_bf16 v[66:69], v[180:183], v[212:215], 0
	v_mfma_f32_16x16x32_bf16 v[114:117], v[176:179], v[192:195], v[114:117]
	v_mfma_f32_16x16x32_bf16 v[106:109], v[184:187], v[192:195], v[106:109]
	v_mfma_f32_16x16x32_bf16 v[98:101], v[176:179], v[200:203], v[98:101]
	v_mfma_f32_16x16x32_bf16 v[90:93], v[184:187], v[200:203], v[90:93]
	v_mfma_f32_16x16x32_bf16 v[82:85], v[176:179], v[208:211], v[82:85]
	v_mfma_f32_16x16x32_bf16 v[74:77], v[184:187], v[208:211], v[74:77]
	v_mfma_f32_16x16x32_bf16 v[70:73], v[176:179], v[216:219], v[70:73]
	v_mfma_f32_16x16x32_bf16 v[66:69], v[184:187], v[216:219], v[66:69]
	s_setprio 0
	s_barrier
	s_add_i32 s63, s53, s43
	v_lshl_add_u64 v[146:147], s[36:37], 0, v[132:133]
	s_mov_b32 m0, s63
	ds_read_b128 v[188:191], v154 offset:16384
	ds_read_b128 v[192:195], v154 offset:17408
	ds_read_b128 v[196:199], v154 offset:18432
	ds_read_b128 v[200:203], v154 offset:19456
	ds_read_b128 v[204:207], v154 offset:20480
	ds_read_b128 v[208:211], v154 offset:21504
	ds_read_b128 v[212:215], v154 offset:22528
	ds_read_b128 v[216:219], v154 offset:23552
	global_load_lds_dwordx4 v[146:147], off
	s_add_i32 m0, s63, 0x2000
	s_add_u32 s64, s36, 0x80000
	v_lshl_add_u64 v[220:221], s[36:37], 0, v[136:137]
	s_addc_u32 s65, s37, 0
	s_add_i32 s63, s54, s43
	global_load_lds_dwordx4 v[220:221], off
	v_lshl_add_u64 v[222:223], s[64:65], 0, v[132:133]
	s_mov_b32 m0, s63
	v_lshl_add_u64 v[224:225], s[38:39], 0, v[134:135]
	global_load_lds_dwordx4 v[222:223], off
	v_lshl_add_u64 v[222:223], s[64:65], 0, v[136:137]
	s_add_i32 m0, s63, 0x2000
	s_nop 0
	global_load_lds_dwordx4 v[222:223], off
	v_lshl_add_u64 v[222:223], s[38:39], 0, v[130:131]
	s_mov_b32 m0, s35
	s_nop 0
	global_load_lds_dwordx4 v[222:223], off
	s_mov_b32 m0, s46
	s_nop 0
	global_load_lds_dwordx4 v[224:225], off
	s_waitcnt vmcnt(8)
	s_waitcnt lgkmcnt(0)
	s_barrier
	s_setprio 1
	s_waitcnt lgkmcnt(0)
	v_mfma_f32_16x16x32_bf16 v[62:65], v[156:159], v[188:191], 0
	v_mfma_f32_16x16x32_bf16 v[58:61], v[164:167], v[188:191], 0
	v_mfma_f32_16x16x32_bf16 v[54:57], v[156:159], v[196:199], 0
	v_mfma_f32_16x16x32_bf16 v[46:49], v[164:167], v[196:199], 0
	v_mfma_f32_16x16x32_bf16 v[38:41], v[156:159], v[204:207], 0
	v_mfma_f32_16x16x32_bf16 v[30:33], v[164:167], v[204:207], 0
	v_mfma_f32_16x16x32_bf16 v[22:25], v[156:159], v[212:215], 0
	v_mfma_f32_16x16x32_bf16 v[14:17], v[164:167], v[212:215], 0
	v_mfma_f32_16x16x32_bf16 v[62:65], v[160:163], v[192:195], v[62:65]
	v_mfma_f32_16x16x32_bf16 v[58:61], v[168:171], v[192:195], v[58:61]
	v_mfma_f32_16x16x32_bf16 v[54:57], v[160:163], v[200:203], v[54:57]
	v_mfma_f32_16x16x32_bf16 v[46:49], v[168:171], v[200:203], v[46:49]
	v_mfma_f32_16x16x32_bf16 v[38:41], v[160:163], v[208:211], v[38:41]
	v_mfma_f32_16x16x32_bf16 v[30:33], v[168:171], v[208:211], v[30:33]
	v_mfma_f32_16x16x32_bf16 v[22:25], v[160:163], v[216:219], v[22:25]
	v_mfma_f32_16x16x32_bf16 v[14:17], v[168:171], v[216:219], v[14:17]
	s_setprio 0
	s_setprio 1
	v_mfma_f32_16x16x32_bf16 v[50:53], v[172:175], v[188:191], 0
	v_mfma_f32_16x16x32_bf16 v[42:45], v[180:183], v[188:191], 0
	v_mfma_f32_16x16x32_bf16 v[34:37], v[172:175], v[196:199], 0
	v_mfma_f32_16x16x32_bf16 v[26:29], v[180:183], v[196:199], 0
	v_mfma_f32_16x16x32_bf16 v[18:21], v[172:175], v[204:207], 0
	v_mfma_f32_16x16x32_bf16 v[10:13], v[180:183], v[204:207], 0
	v_mfma_f32_16x16x32_bf16 v[6:9], v[172:175], v[212:215], 0
	v_mfma_f32_16x16x32_bf16 v[2:5], v[180:183], v[212:215], 0
	v_mfma_f32_16x16x32_bf16 v[50:53], v[176:179], v[192:195], v[50:53]
	v_mfma_f32_16x16x32_bf16 v[42:45], v[184:187], v[192:195], v[42:45]
	v_mfma_f32_16x16x32_bf16 v[34:37], v[176:179], v[200:203], v[34:37]
	v_mfma_f32_16x16x32_bf16 v[26:29], v[184:187], v[200:203], v[26:29]
	v_mfma_f32_16x16x32_bf16 v[18:21], v[176:179], v[208:211], v[18:21]
	v_mfma_f32_16x16x32_bf16 v[10:13], v[184:187], v[208:211], v[10:13]
	v_mfma_f32_16x16x32_bf16 v[6:9], v[176:179], v[216:219], v[6:9]
	v_mfma_f32_16x16x32_bf16 v[2:5], v[184:187], v[216:219], v[2:5]
	s_setprio 0
	s_barrier
	s_add_i32 s63, 0, 0x18000
	v_add_u32_e32 v155, s63, v150
	s_add_i32 s64, 0, 0x1c000
	ds_read_b128 v[156:159], v155
	ds_read_b128 v[160:163], v155 offset:1024
	ds_read_b128 v[164:167], v155 offset:2048
	ds_read_b128 v[168:171], v155 offset:3072
	v_add_u32_e32 v155, s64, v150
	ds_read_b128 v[172:175], v155
	ds_read_b128 v[176:179], v155 offset:1024
	ds_read_b128 v[180:183], v155 offset:2048
	ds_read_b128 v[184:187], v155 offset:3072
	s_add_u32 s38, s38, 0x20000
	s_addc_u32 s39, s39, 0
	s_mov_b32 m0, s47
	v_lshl_add_u64 v[226:227], s[38:39], 0, v[130:131]
	ds_read_b128 v[188:191], v154 offset:32768
	ds_read_b128 v[192:195], v154 offset:33792
	ds_read_b128 v[196:199], v154 offset:34816
	ds_read_b128 v[200:203], v154 offset:35840
	ds_read_b128 v[204:207], v154 offset:36864
	ds_read_b128 v[208:211], v154 offset:37888
	ds_read_b128 v[212:215], v154 offset:38912
	ds_read_b128 v[216:219], v154 offset:39936
	global_load_lds_dwordx4 v[226:227], off
	v_lshl_add_u64 v[226:227], s[38:39], 0, v[134:135]
	s_mov_b32 m0, s48
	s_nop 0
	global_load_lds_dwordx4 v[226:227], off
	s_waitcnt vmcnt(8)
	s_waitcnt lgkmcnt(0)
	s_barrier
	s_setprio 1
	s_waitcnt lgkmcnt(0)
	v_mfma_f32_16x16x32_bf16 v[126:129], v[156:159], v[188:191], v[126:129]
	v_mfma_f32_16x16x32_bf16 v[122:125], v[164:167], v[188:191], v[122:125]
	v_mfma_f32_16x16x32_bf16 v[118:121], v[156:159], v[196:199], v[118:121]
	v_mfma_f32_16x16x32_bf16 v[110:113], v[164:167], v[196:199], v[110:113]
	v_mfma_f32_16x16x32_bf16 v[102:105], v[156:159], v[204:207], v[102:105]
	v_mfma_f32_16x16x32_bf16 v[94:97], v[164:167], v[204:207], v[94:97]
	v_mfma_f32_16x16x32_bf16 v[86:89], v[156:159], v[212:215], v[86:89]
	v_mfma_f32_16x16x32_bf16 v[78:81], v[164:167], v[212:215], v[78:81]
	v_mfma_f32_16x16x32_bf16 v[126:129], v[160:163], v[192:195], v[126:129]
	v_mfma_f32_16x16x32_bf16 v[122:125], v[168:171], v[192:195], v[122:125]
	v_mfma_f32_16x16x32_bf16 v[118:121], v[160:163], v[200:203], v[118:121]
	v_mfma_f32_16x16x32_bf16 v[110:113], v[168:171], v[200:203], v[110:113]
	v_mfma_f32_16x16x32_bf16 v[102:105], v[160:163], v[208:211], v[102:105]
	v_mfma_f32_16x16x32_bf16 v[94:97], v[168:171], v[208:211], v[94:97]
	v_mfma_f32_16x16x32_bf16 v[86:89], v[160:163], v[216:219], v[86:89]
	v_mfma_f32_16x16x32_bf16 v[78:81], v[168:171], v[216:219], v[78:81]
	s_setprio 0
	s_setprio 1
	v_mfma_f32_16x16x32_bf16 v[114:117], v[172:175], v[188:191], v[114:117]
	v_mfma_f32_16x16x32_bf16 v[106:109], v[180:183], v[188:191], v[106:109]
	v_mfma_f32_16x16x32_bf16 v[98:101], v[172:175], v[196:199], v[98:101]
	v_mfma_f32_16x16x32_bf16 v[90:93], v[180:183], v[196:199], v[90:93]
	v_mfma_f32_16x16x32_bf16 v[82:85], v[172:175], v[204:207], v[82:85]
	v_mfma_f32_16x16x32_bf16 v[74:77], v[180:183], v[204:207], v[74:77]
	v_mfma_f32_16x16x32_bf16 v[70:73], v[172:175], v[212:215], v[70:73]
	v_mfma_f32_16x16x32_bf16 v[66:69], v[180:183], v[212:215], v[66:69]
	v_mfma_f32_16x16x32_bf16 v[114:117], v[176:179], v[192:195], v[114:117]
	v_mfma_f32_16x16x32_bf16 v[106:109], v[184:187], v[192:195], v[106:109]
	v_mfma_f32_16x16x32_bf16 v[98:101], v[176:179], v[200:203], v[98:101]
	v_mfma_f32_16x16x32_bf16 v[90:93], v[184:187], v[200:203], v[90:93]
	v_mfma_f32_16x16x32_bf16 v[82:85], v[176:179], v[208:211], v[82:85]
	v_mfma_f32_16x16x32_bf16 v[74:77], v[184:187], v[208:211], v[74:77]
	v_mfma_f32_16x16x32_bf16 v[70:73], v[176:179], v[216:219], v[70:73]
	v_mfma_f32_16x16x32_bf16 v[66:69], v[184:187], v[216:219], v[66:69]
	s_setprio 0
	s_barrier
	s_add_i32 s38, s63, s43
	v_lshl_add_u64 v[146:147], v[146:147], 0, s[8:9]
	s_mov_b32 m0, s38
	ds_read_b128 v[188:191], v154 offset:49152
	ds_read_b128 v[192:195], v154 offset:50176
	ds_read_b128 v[196:199], v154 offset:51200
	ds_read_b128 v[200:203], v154 offset:52224
	ds_read_b128 v[204:207], v154 offset:53248
	ds_read_b128 v[208:211], v154 offset:54272
	ds_read_b128 v[212:215], v154 offset:55296
	ds_read_b128 v[216:219], v154 offset:56320
	global_load_lds_dwordx4 v[146:147], off
	s_add_i32 m0, s38, 0x2000
	s_add_u32 s36, s36, 0x80080
	v_lshl_add_u64 v[146:147], v[220:221], 0, s[8:9]
	s_addc_u32 s37, s37, 0
	s_add_i32 s38, s64, s43
	global_load_lds_dwordx4 v[146:147], off
	v_lshl_add_u64 v[146:147], s[36:37], 0, v[132:133]
	s_mov_b32 m0, s38
	s_nop 0
	global_load_lds_dwordx4 v[146:147], off
	v_lshl_add_u64 v[146:147], s[36:37], 0, v[136:137]
	s_add_i32 m0, s38, 0x2000
	s_nop 0
	global_load_lds_dwordx4 v[146:147], off
	v_lshl_add_u64 v[146:147], v[222:223], 0, s[8:9]
	s_mov_b32 m0, s50
	s_nop 0
	global_load_lds_dwordx4 v[146:147], off
	v_lshl_add_u64 v[146:147], v[224:225], 0, s[8:9]
	s_mov_b32 m0, s51
	s_nop 0
	global_load_lds_dwordx4 v[146:147], off
	s_waitcnt vmcnt(8)
	s_waitcnt lgkmcnt(0)
	s_barrier
	s_setprio 1
	s_waitcnt lgkmcnt(0)
	v_mfma_f32_16x16x32_bf16 v[62:65], v[156:159], v[188:191], v[62:65]
	v_mfma_f32_16x16x32_bf16 v[58:61], v[164:167], v[188:191], v[58:61]
	v_mfma_f32_16x16x32_bf16 v[54:57], v[156:159], v[196:199], v[54:57]
	v_mfma_f32_16x16x32_bf16 v[46:49], v[164:167], v[196:199], v[46:49]
	v_mfma_f32_16x16x32_bf16 v[38:41], v[156:159], v[204:207], v[38:41]
	v_mfma_f32_16x16x32_bf16 v[30:33], v[164:167], v[204:207], v[30:33]
	v_mfma_f32_16x16x32_bf16 v[22:25], v[156:159], v[212:215], v[22:25]
	v_mfma_f32_16x16x32_bf16 v[14:17], v[164:167], v[212:215], v[14:17]
	v_mfma_f32_16x16x32_bf16 v[62:65], v[160:163], v[192:195], v[62:65]
	v_mfma_f32_16x16x32_bf16 v[58:61], v[168:171], v[192:195], v[58:61]
	v_mfma_f32_16x16x32_bf16 v[54:57], v[160:163], v[200:203], v[54:57]
	v_mfma_f32_16x16x32_bf16 v[46:49], v[168:171], v[200:203], v[46:49]
	v_mfma_f32_16x16x32_bf16 v[38:41], v[160:163], v[208:211], v[38:41]
	v_mfma_f32_16x16x32_bf16 v[30:33], v[168:171], v[208:211], v[30:33]
	v_mfma_f32_16x16x32_bf16 v[22:25], v[160:163], v[216:219], v[22:25]
	v_mfma_f32_16x16x32_bf16 v[14:17], v[168:171], v[216:219], v[14:17]
	s_setprio 0
	s_setprio 1
	v_mfma_f32_16x16x32_bf16 v[50:53], v[172:175], v[188:191], v[50:53]
	v_mfma_f32_16x16x32_bf16 v[42:45], v[180:183], v[188:191], v[42:45]
	v_mfma_f32_16x16x32_bf16 v[34:37], v[172:175], v[196:199], v[34:37]
	v_mfma_f32_16x16x32_bf16 v[26:29], v[180:183], v[196:199], v[26:29]
	v_mfma_f32_16x16x32_bf16 v[18:21], v[172:175], v[204:207], v[18:21]
	v_mfma_f32_16x16x32_bf16 v[10:13], v[180:183], v[204:207], v[10:13]
	v_mfma_f32_16x16x32_bf16 v[6:9], v[172:175], v[212:215], v[6:9]
	v_mfma_f32_16x16x32_bf16 v[2:5], v[180:183], v[212:215], v[2:5]
	v_mfma_f32_16x16x32_bf16 v[50:53], v[176:179], v[192:195], v[50:53]
	v_mfma_f32_16x16x32_bf16 v[42:45], v[184:187], v[192:195], v[42:45]
	v_mfma_f32_16x16x32_bf16 v[34:37], v[176:179], v[200:203], v[34:37]
	v_mfma_f32_16x16x32_bf16 v[26:29], v[184:187], v[200:203], v[26:29]
	v_mfma_f32_16x16x32_bf16 v[18:21], v[176:179], v[208:211], v[18:21]
	v_mfma_f32_16x16x32_bf16 v[10:13], v[184:187], v[208:211], v[10:13]
	v_mfma_f32_16x16x32_bf16 v[6:9], v[176:179], v[216:219], v[6:9]
	v_mfma_f32_16x16x32_bf16 v[2:5], v[184:187], v[216:219], v[2:5]
	s_setprio 0
	s_barrier
	s_add_i32 s62, s62, 2
	s_add_u32 s0, s0, 0x100
	s_addc_u32 s1, s1, 0
	s_add_u32 s60, s60, 0x100
	s_addc_u32 s61, s61, 0

.LBB0_275:
	v_lshrrev_b32_e32 v18, 1, v5
	v_and_b32_e32 v18, 24, v18
	v_and_b32_e32 v9, 15, v5
	v_lshlrev_b32_e32 v19, 1, v18
	v_lshlrev_b32_e32 v5, 2, v5
	v_mov_b32_e32 v133, v155
	v_lshl_or_b32 v168, s9, 6, v9
	v_lshl_or_b32 v9, v9, 6, v19
	s_lshl_b32 s9, s9, 13
	v_and_b32_e32 v5, 32, v5
	v_lshl_add_u64 v[10:11], s[10:11], 0, v[132:133]
	v_mov_b32_e32 v137, v155
	v_bitop3_b32 v19, v9, s9, v5 bitop3:0xde
	s_lshl_b32 s9, s12, 5
	v_lshl_add_u64 v[12:13], s[10:11], 0, v[136:137]
	v_mov_b32_e32 v131, v155
	s_and_b32 s9, s9, 0x60
	s_add_i32 m0, s81, 0x18000
	v_lshl_add_u64 v[10:11], v[10:11], 0, s[34:35]
	v_lshl_add_u64 v[14:15], s[60:61], 0, v[130:131]
	v_mov_b32_e32 v135, v155
	s_lshl_b32 s12, s9, 7
	s_waitcnt vmcnt(2)
	s_barrier
	global_load_lds_dwordx4 v[10:11], off
	v_lshl_add_u64 v[10:11], v[12:13], 0, s[34:35]
	s_add_i32 m0, s81, 0x1a000
	s_add_i32 s85, s81, 0x8000
	s_add_i32 s86, s81, 0xa000
	v_lshl_add_u64 v[16:17], s[60:61], 0, v[134:135]
	v_bitop3_b32 v169, v9, s12, v5 bitop3:0xde
	global_load_lds_dwordx4 v[10:11], off
	v_lshl_add_u64 v[10:11], v[14:15], 0, s[34:35]
	s_mov_b32 m0, s85
	s_add_u32 s12, s10, 0x80080
	global_load_lds_dwordx4 v[10:11], off
	v_lshl_add_u64 v[10:11], v[16:17], 0, s[34:35]
	s_mov_b32 m0, s86
	s_addc_u32 s13, s11, 0
	global_load_lds_dwordx4 v[10:11], off
	s_add_i32 m0, s81, 0x1c000
	v_lshl_add_u64 v[10:11], s[12:13], 0, v[132:133]
	global_load_lds_dwordx4 v[10:11], off
	v_lshl_add_u64 v[10:11], s[12:13], 0, v[136:137]
	s_add_i32 m0, s81, 0x1e000
	v_lshlrev_b32_e32 v5, 15, v2
	global_load_lds_dwordx4 v[10:11], off
	v_and_b32_e32 v5, 0xffff0000, v5
	v_lshl_add_u32 v3, v3, 12, v5
	v_and_b32_e32 v2, 1, v2
	v_lshl_or_b32 v2, v2, 6, v3
	v_lshl_add_u32 v138, v4, 1, v2
	v_lshlrev_b32_e32 v2, 15, v6
	v_and_b32_e32 v2, 0xffff0000, v2
	s_cmpk_lt_u32 s8, 0x100
	v_or_b32_e32 v170, s9, v18
	v_lshl_add_u32 v2, v7, 12, v2
	v_and_b32_e32 v3, 1, v6
	v_readlane_b32 s8, v241, 26
	s_waitcnt vmcnt(6)
	v_lshl_or_b32 v2, v3, 6, v2
	v_readlane_b32 s9, v241, 27
	v_lshl_add_u32 v140, v8, 1, v2
	v_mov_b32_e32 v2, 0
	s_mov_b32 s87, s8
	v_readlane_b32 s8, v241, 20
	s_cselect_b64 s[56:57], -1, 0
	v_mov_b32_e32 v139, v155
	v_mov_b32_e32 v141, v155
	s_mov_b32 s92, 0
	v_add_u32_e32 v171, 0, v19
	s_mov_b32 s91, s8
	s_nop 0
	s_barrier
	v_readlane_b32 s9, v241, 21
	s_branch .LBB0_277
.LBB0_276:
	v_mov_b32_e32 v2, 0
	s_mov_b32 s87, s66
	s_mov_b32 s91, s62
	s_nop 0
	s_mov_b64 s[60:61], s[46:47]
	s_mov_b32 s92, s93
	s_andn2_b64 vcc, exec, s[36:37]
	s_mov_b64 s[10:11], s[8:9]
	s_cbranch_vccz .LBB0_329

.LBB0_289:
	s_add_i32 s62, s62, s89
	s_add_u32 s28, s10, 0x100
	s_addc_u32 s29, s11, 0
	s_ashr_i32 s63, s62, 31
	s_lshl_b64 s[8:9], s[62:63], 20
	s_add_u32 s46, s48, s8
	s_addc_u32 s47, s49, s9
	s_and_b64 s[8:9], s[38:39], exec
	s_cselect_b32 s63, s47, s61
	s_cselect_b32 s94, s46, s60
	s_ashr_i32 s67, s66, 31
	s_lshl_b64 s[8:9], s[66:67], 20
	s_add_u32 s8, s30, s8
	s_addc_u32 s9, s65, s9
	s_and_b64 s[12:13], s[38:39], exec
	s_cselect_b32 s67, s9, s11
	s_cselect_b32 s95, s8, s10
	s_add_u32 s10, s60, 0x80080
	s_addc_u32 s11, s61, 0
	v_lshl_add_u64 v[142:143], s[10:11], 0, v[138:139]
	v_lshl_add_u64 v[144:145], s[10:11], 0, v[140:141]
	s_mov_b32 s96, -2
	s_mov_b64 s[10:11], 0
	s_add_u32 s12, s60, s10
	s_addc_u32 s13, s61, s11
	s_add_u32 s12, s12, 0x100
	s_addc_u32 s13, s13, 0
	s_add_u32 s97, s28, s10
	s_addc_u32 vcc_lo, s29, s11
	s_add_i32 vcc_hi, 0, 0x10000
	s_cmpk_eq_i32 s10, 0xf00
	s_cselect_b32 s41, s63, s13
	s_cselect_b32 s40, s94, s12
	v_add_u32_e32 v154, vcc_hi, v169
	s_cselect_b32 s13, s67, vcc_lo
	s_cselect_b32 s12, s95, s97
	s_add_i32 s97, 0, 0x14000
	ds_read_b128 v[146:149], v154
	ds_read_b128 v[150:153], v154 offset:1024
	ds_read_b128 v[164:167], v154 offset:2048
	ds_read_b128 v[172:175], v154 offset:3072
	v_add_u32_e32 v154, s97, v169
	ds_read_b128 v[176:179], v154
	ds_read_b128 v[180:183], v154 offset:1024
	ds_read_b128 v[184:187], v154 offset:2048
	ds_read_b128 v[188:191], v154 offset:3072
	v_lshl_add_u64 v[196:197], v[142:143], 0, s[10:11]
	s_add_i32 m0, s81, 0xc000
	ds_read_b128 v[200:203], v171
	ds_read_b128 v[204:207], v171 offset:1024
	ds_read_b128 v[208:211], v171 offset:2048
	ds_read_b128 v[212:215], v171 offset:3072
	ds_read_b128 v[216:219], v171 offset:4096
	ds_read_b128 v[220:223], v171 offset:5120
	ds_read_b128 v[224:227], v171 offset:6144
	ds_read_b128 v[228:231], v171 offset:7168
	global_load_lds_dwordx4 v[196:197], off
	v_lshl_add_u64 v[196:197], v[144:145], 0, s[10:11]
	s_add_i32 m0, s81, 0xe000
	s_nop 0
	global_load_lds_dwordx4 v[196:197], off
	s_waitcnt vmcnt(8)
	s_waitcnt lgkmcnt(0)
	s_barrier
	s_setprio 1
	s_waitcnt lgkmcnt(0)
	v_mfma_f32_16x16x32_bf16 v[126:129], v[146:149], v[200:203], 0
	v_mfma_f32_16x16x32_bf16 v[122:125], v[164:167], v[200:203], 0
	v_mfma_f32_16x16x32_bf16 v[118:121], v[146:149], v[208:211], 0
	v_mfma_f32_16x16x32_bf16 v[114:117], v[164:167], v[208:211], 0
	v_mfma_f32_16x16x32_bf16 v[110:113], v[146:149], v[216:219], 0
	v_mfma_f32_16x16x32_bf16 v[106:109], v[164:167], v[216:219], 0
	v_mfma_f32_16x16x32_bf16 v[102:105], v[146:149], v[224:227], 0
	v_mfma_f32_16x16x32_bf16 v[98:101], v[164:167], v[224:227], 0
	v_mfma_f32_16x16x32_bf16 v[126:129], v[150:153], v[204:207], v[126:129]
	v_mfma_f32_16x16x32_bf16 v[122:125], v[172:175], v[204:207], v[122:125]
	v_mfma_f32_16x16x32_bf16 v[118:121], v[150:153], v[212:215], v[118:121]
	v_mfma_f32_16x16x32_bf16 v[114:117], v[172:175], v[212:215], v[114:117]
	v_mfma_f32_16x16x32_bf16 v[110:113], v[150:153], v[220:223], v[110:113]
	v_mfma_f32_16x16x32_bf16 v[106:109], v[172:175], v[220:223], v[106:109]
	v_mfma_f32_16x16x32_bf16 v[102:105], v[150:153], v[228:231], v[102:105]
	v_mfma_f32_16x16x32_bf16 v[98:101], v[172:175], v[228:231], v[98:101]
	s_setprio 0
	s_setprio 1
	v_mfma_f32_16x16x32_bf16 v[94:97], v[176:179], v[200:203], 0
	v_mfma_f32_16x16x32_bf16 v[90:93], v[184:187], v[200:203], 0
	v_mfma_f32_16x16x32_bf16 v[86:89], v[176:179], v[208:211], 0
	v_mfma_f32_16x16x32_bf16 v[82:85], v[184:187], v[208:211], 0
	v_mfma_f32_16x16x32_bf16 v[78:81], v[176:179], v[216:219], 0
	v_mfma_f32_16x16x32_bf16 v[74:77], v[184:187], v[216:219], 0
	v_mfma_f32_16x16x32_bf16 v[70:73], v[176:179], v[224:227], 0
	v_mfma_f32_16x16x32_bf16 v[66:69], v[184:187], v[224:227], 0
	v_mfma_f32_16x16x32_bf16 v[94:97], v[180:183], v[204:207], v[94:97]
	v_mfma_f32_16x16x32_bf16 v[90:93], v[188:191], v[204:207], v[90:93]
	v_mfma_f32_16x16x32_bf16 v[86:89], v[180:183], v[212:215], v[86:89]
	v_mfma_f32_16x16x32_bf16 v[82:85], v[188:191], v[212:215], v[82:85]
	v_mfma_f32_16x16x32_bf16 v[78:81], v[180:183], v[220:223], v[78:81]
	v_mfma_f32_16x16x32_bf16 v[74:77], v[188:191], v[220:223], v[74:77]
	v_mfma_f32_16x16x32_bf16 v[70:73], v[180:183], v[228:231], v[70:73]
	v_mfma_f32_16x16x32_bf16 v[66:69], v[188:191], v[228:231], v[66:69]
	s_setprio 0
	s_barrier
	s_add_i32 vcc_lo, vcc_hi, s80
	v_lshl_add_u64 v[196:197], s[12:13], 0, v[132:133]
	s_mov_b32 m0, vcc_lo
	ds_read_b128 v[200:203], v171 offset:16384
	ds_read_b128 v[204:207], v171 offset:17408
	ds_read_b128 v[208:211], v171 offset:18432
	ds_read_b128 v[212:215], v171 offset:19456
	ds_read_b128 v[216:219], v171 offset:20480
	ds_read_b128 v[220:223], v171 offset:21504
	ds_read_b128 v[224:227], v171 offset:22528
	ds_read_b128 v[228:231], v171 offset:23552
	global_load_lds_dwordx4 v[196:197], off
	s_add_i32 m0, vcc_lo, 0x2000
	s_add_u32 vcc_lo, s12, 0x80000
	v_lshl_add_u64 v[232:233], s[12:13], 0, v[136:137]
	s_addc_u32 vcc_hi, s13, 0
	s_add_i32 s97, s97, s80
	global_load_lds_dwordx4 v[232:233], off
	v_lshl_add_u64 v[234:235], vcc, 0, v[132:133]
	s_mov_b32 m0, s97
	v_lshl_add_u64 v[236:237], s[40:41], 0, v[134:135]
	global_load_lds_dwordx4 v[234:235], off
	v_lshl_add_u64 v[234:235], vcc, 0, v[136:137]
	s_add_i32 m0, s97, 0x2000
	s_nop 0
	global_load_lds_dwordx4 v[234:235], off
	v_lshl_add_u64 v[234:235], s[40:41], 0, v[130:131]
	s_mov_b32 m0, s81
	s_nop 0
	global_load_lds_dwordx4 v[234:235], off
	s_mov_b32 m0, s82
	s_nop 0
	global_load_lds_dwordx4 v[236:237], off
	s_waitcnt vmcnt(8)
	s_waitcnt lgkmcnt(0)
	s_barrier
	s_setprio 1
	s_waitcnt lgkmcnt(0)
	v_mfma_f32_16x16x32_bf16 v[62:65], v[146:149], v[200:203], 0
	v_mfma_f32_16x16x32_bf16 v[58:61], v[164:167], v[200:203], 0
	v_mfma_f32_16x16x32_bf16 v[54:57], v[146:149], v[208:211], 0
	v_mfma_f32_16x16x32_bf16 v[50:53], v[164:167], v[208:211], 0
	v_mfma_f32_16x16x32_bf16 v[46:49], v[146:149], v[216:219], 0
	v_mfma_f32_16x16x32_bf16 v[42:45], v[164:167], v[216:219], 0
	v_mfma_f32_16x16x32_bf16 v[38:41], v[146:149], v[224:227], 0
	v_mfma_f32_16x16x32_bf16 v[34:37], v[164:167], v[224:227], 0
	v_mfma_f32_16x16x32_bf16 v[62:65], v[150:153], v[204:207], v[62:65]
	v_mfma_f32_16x16x32_bf16 v[58:61], v[172:175], v[204:207], v[58:61]
	v_mfma_f32_16x16x32_bf16 v[54:57], v[150:153], v[212:215], v[54:57]
	v_mfma_f32_16x16x32_bf16 v[50:53], v[172:175], v[212:215], v[50:53]
	v_mfma_f32_16x16x32_bf16 v[46:49], v[150:153], v[220:223], v[46:49]
	v_mfma_f32_16x16x32_bf16 v[42:45], v[172:175], v[220:223], v[42:45]
	v_mfma_f32_16x16x32_bf16 v[38:41], v[150:153], v[228:231], v[38:41]
	v_mfma_f32_16x16x32_bf16 v[34:37], v[172:175], v[228:231], v[34:37]
	s_setprio 0
	s_setprio 1
	v_mfma_f32_16x16x32_bf16 v[30:33], v[176:179], v[200:203], 0
	v_mfma_f32_16x16x32_bf16 v[26:29], v[184:187], v[200:203], 0
	v_mfma_f32_16x16x32_bf16 v[22:25], v[176:179], v[208:211], 0
	v_mfma_f32_16x16x32_bf16 v[18:21], v[184:187], v[208:211], 0
	v_mfma_f32_16x16x32_bf16 v[14:17], v[176:179], v[216:219], 0
	v_mfma_f32_16x16x32_bf16 v[10:13], v[184:187], v[216:219], 0
	v_mfma_f32_16x16x32_bf16 v[6:9], v[176:179], v[224:227], 0
	v_mfma_f32_16x16x32_bf16 v[2:5], v[184:187], v[224:227], 0
	v_mfma_f32_16x16x32_bf16 v[30:33], v[180:183], v[204:207], v[30:33]
	v_mfma_f32_16x16x32_bf16 v[26:29], v[188:191], v[204:207], v[26:29]
	v_mfma_f32_16x16x32_bf16 v[22:25], v[180:183], v[212:215], v[22:25]
	v_mfma_f32_16x16x32_bf16 v[18:21], v[188:191], v[212:215], v[18:21]
	v_mfma_f32_16x16x32_bf16 v[14:17], v[180:183], v[220:223], v[14:17]
	v_mfma_f32_16x16x32_bf16 v[10:13], v[188:191], v[220:223], v[10:13]
	v_mfma_f32_16x16x32_bf16 v[6:9], v[180:183], v[228:231], v[6:9]
	v_mfma_f32_16x16x32_bf16 v[2:5], v[188:191], v[228:231], v[2:5]
	s_setprio 0
	s_barrier
	s_add_i32 s97, 0, 0x18000
	v_add_u32_e32 v154, s97, v169
	s_add_i32 vcc_lo, 0, 0x1c000
	ds_read_b128 v[146:149], v154
	ds_read_b128 v[150:153], v154 offset:1024
	ds_read_b128 v[164:167], v154 offset:2048
	ds_read_b128 v[172:175], v154 offset:3072
	v_add_u32_e32 v154, vcc_lo, v169
	ds_read_b128 v[176:179], v154
	ds_read_b128 v[180:183], v154 offset:1024
	ds_read_b128 v[184:187], v154 offset:2048
	ds_read_b128 v[188:191], v154 offset:3072
	s_add_u32 s40, s40, 0x80000
	s_addc_u32 s41, s41, 0
	s_mov_b32 m0, s83
	v_lshl_add_u64 v[238:239], s[40:41], 0, v[130:131]
	ds_read_b128 v[200:203], v171 offset:32768
	ds_read_b128 v[204:207], v171 offset:33792
	ds_read_b128 v[208:211], v171 offset:34816
	ds_read_b128 v[212:215], v171 offset:35840
	ds_read_b128 v[216:219], v171 offset:36864
	ds_read_b128 v[220:223], v171 offset:37888
	ds_read_b128 v[224:227], v171 offset:38912
	ds_read_b128 v[228:231], v171 offset:39936
	global_load_lds_dwordx4 v[238:239], off
	v_lshl_add_u64 v[238:239], s[40:41], 0, v[134:135]
	s_mov_b32 m0, s84
	s_nop 0
	global_load_lds_dwordx4 v[238:239], off
	s_waitcnt vmcnt(8)
	s_waitcnt lgkmcnt(0)
	s_barrier
	s_setprio 1
	s_waitcnt lgkmcnt(0)
	v_mfma_f32_16x16x32_bf16 v[126:129], v[146:149], v[200:203], v[126:129]
	v_mfma_f32_16x16x32_bf16 v[122:125], v[164:167], v[200:203], v[122:125]
	v_mfma_f32_16x16x32_bf16 v[118:121], v[146:149], v[208:211], v[118:121]
	v_mfma_f32_16x16x32_bf16 v[114:117], v[164:167], v[208:211], v[114:117]
	v_mfma_f32_16x16x32_bf16 v[110:113], v[146:149], v[216:219], v[110:113]
	v_mfma_f32_16x16x32_bf16 v[106:109], v[164:167], v[216:219], v[106:109]
	v_mfma_f32_16x16x32_bf16 v[102:105], v[146:149], v[224:227], v[102:105]
	v_mfma_f32_16x16x32_bf16 v[98:101], v[164:167], v[224:227], v[98:101]
	v_mfma_f32_16x16x32_bf16 v[126:129], v[150:153], v[204:207], v[126:129]
	v_mfma_f32_16x16x32_bf16 v[122:125], v[172:175], v[204:207], v[122:125]
	v_mfma_f32_16x16x32_bf16 v[118:121], v[150:153], v[212:215], v[118:121]
	v_mfma_f32_16x16x32_bf16 v[114:117], v[172:175], v[212:215], v[114:117]
	v_mfma_f32_16x16x32_bf16 v[110:113], v[150:153], v[220:223], v[110:113]
	v_mfma_f32_16x16x32_bf16 v[106:109], v[172:175], v[220:223], v[106:109]
	v_mfma_f32_16x16x32_bf16 v[102:105], v[150:153], v[228:231], v[102:105]
	v_mfma_f32_16x16x32_bf16 v[98:101], v[172:175], v[228:231], v[98:101]
	s_setprio 0
	s_setprio 1
	v_mfma_f32_16x16x32_bf16 v[94:97], v[176:179], v[200:203], v[94:97]
	v_mfma_f32_16x16x32_bf16 v[90:93], v[184:187], v[200:203], v[90:93]
	v_mfma_f32_16x16x32_bf16 v[86:89], v[176:179], v[208:211], v[86:89]
	v_mfma_f32_16x16x32_bf16 v[82:85], v[184:187], v[208:211], v[82:85]
	v_mfma_f32_16x16x32_bf16 v[78:81], v[176:179], v[216:219], v[78:81]
	v_mfma_f32_16x16x32_bf16 v[74:77], v[184:187], v[216:219], v[74:77]
	v_mfma_f32_16x16x32_bf16 v[70:73], v[176:179], v[224:227], v[70:73]
	v_mfma_f32_16x16x32_bf16 v[66:69], v[184:187], v[224:227], v[66:69]
	v_mfma_f32_16x16x32_bf16 v[94:97], v[180:183], v[204:207], v[94:97]
	v_mfma_f32_16x16x32_bf16 v[90:93], v[188:191], v[204:207], v[90:93]
	v_mfma_f32_16x16x32_bf16 v[86:89], v[180:183], v[212:215], v[86:89]
	v_mfma_f32_16x16x32_bf16 v[82:85], v[188:191], v[212:215], v[82:85]
	v_mfma_f32_16x16x32_bf16 v[78:81], v[180:183], v[220:223], v[78:81]
	v_mfma_f32_16x16x32_bf16 v[74:77], v[188:191], v[220:223], v[74:77]
	v_mfma_f32_16x16x32_bf16 v[70:73], v[180:183], v[228:231], v[70:73]
	v_mfma_f32_16x16x32_bf16 v[66:69], v[188:191], v[228:231], v[66:69]
	s_setprio 0
	s_barrier
	s_add_i32 s40, s97, s80
	v_lshl_add_u64 v[196:197], v[196:197], 0, s[34:35]
	s_mov_b32 m0, s40
	ds_read_b128 v[200:203], v171 offset:49152
	ds_read_b128 v[204:207], v171 offset:50176
	ds_read_b128 v[208:211], v171 offset:51200
	ds_read_b128 v[212:215], v171 offset:52224
	ds_read_b128 v[216:219], v171 offset:53248
	ds_read_b128 v[220:223], v171 offset:54272
	ds_read_b128 v[224:227], v171 offset:55296
	ds_read_b128 v[228:231], v171 offset:56320
	global_load_lds_dwordx4 v[196:197], off
	s_add_i32 m0, s40, 0x2000
	s_add_u32 s12, s12, 0x80080
	v_lshl_add_u64 v[196:197], v[232:233], 0, s[34:35]
	s_addc_u32 s13, s13, 0
	s_add_i32 s40, vcc_lo, s80
	global_load_lds_dwordx4 v[196:197], off
	v_lshl_add_u64 v[196:197], s[12:13], 0, v[132:133]
	s_mov_b32 m0, s40
	s_nop 0
	global_load_lds_dwordx4 v[196:197], off
	v_lshl_add_u64 v[196:197], s[12:13], 0, v[136:137]
	s_add_i32 m0, s40, 0x2000
	s_nop 0
	global_load_lds_dwordx4 v[196:197], off
	v_lshl_add_u64 v[196:197], v[234:235], 0, s[34:35]
	s_mov_b32 m0, s85
	s_nop 0
	global_load_lds_dwordx4 v[196:197], off
	v_lshl_add_u64 v[196:197], v[236:237], 0, s[34:35]
	s_mov_b32 m0, s86
	s_nop 0
	global_load_lds_dwordx4 v[196:197], off
	s_waitcnt vmcnt(8)
	s_waitcnt lgkmcnt(0)
	s_barrier
	s_setprio 1
	s_waitcnt lgkmcnt(0)
	v_mfma_f32_16x16x32_bf16 v[62:65], v[146:149], v[200:203], v[62:65]
	v_mfma_f32_16x16x32_bf16 v[58:61], v[164:167], v[200:203], v[58:61]
	v_mfma_f32_16x16x32_bf16 v[54:57], v[146:149], v[208:211], v[54:57]
	v_mfma_f32_16x16x32_bf16 v[50:53], v[164:167], v[208:211], v[50:53]
	v_mfma_f32_16x16x32_bf16 v[46:49], v[146:149], v[216:219], v[46:49]
	v_mfma_f32_16x16x32_bf16 v[42:45], v[164:167], v[216:219], v[42:45]
	v_mfma_f32_16x16x32_bf16 v[38:41], v[146:149], v[224:227], v[38:41]
	v_mfma_f32_16x16x32_bf16 v[34:37], v[164:167], v[224:227], v[34:37]
	v_mfma_f32_16x16x32_bf16 v[62:65], v[150:153], v[204:207], v[62:65]
	v_mfma_f32_16x16x32_bf16 v[58:61], v[172:175], v[204:207], v[58:61]
	v_mfma_f32_16x16x32_bf16 v[54:57], v[150:153], v[212:215], v[54:57]
	v_mfma_f32_16x16x32_bf16 v[50:53], v[172:175], v[212:215], v[50:53]
	v_mfma_f32_16x16x32_bf16 v[46:49], v[150:153], v[220:223], v[46:49]
	v_mfma_f32_16x16x32_bf16 v[42:45], v[172:175], v[220:223], v[42:45]
	v_mfma_f32_16x16x32_bf16 v[38:41], v[150:153], v[228:231], v[38:41]
	v_mfma_f32_16x16x32_bf16 v[34:37], v[172:175], v[228:231], v[34:37]
	s_setprio 0
	s_setprio 1
	v_mfma_f32_16x16x32_bf16 v[30:33], v[176:179], v[200:203], v[30:33]
	v_mfma_f32_16x16x32_bf16 v[26:29], v[184:187], v[200:203], v[26:29]
	v_mfma_f32_16x16x32_bf16 v[22:25], v[176:179], v[208:211], v[22:25]
	v_mfma_f32_16x16x32_bf16 v[18:21], v[184:187], v[208:211], v[18:21]
	v_mfma_f32_16x16x32_bf16 v[14:17], v[176:179], v[216:219], v[14:17]
	v_mfma_f32_16x16x32_bf16 v[10:13], v[184:187], v[216:219], v[10:13]
	v_mfma_f32_16x16x32_bf16 v[6:9], v[176:179], v[224:227], v[6:9]
	v_mfma_f32_16x16x32_bf16 v[2:5], v[184:187], v[224:227], v[2:5]
	v_mfma_f32_16x16x32_bf16 v[30:33], v[180:183], v[204:207], v[30:33]
	v_mfma_f32_16x16x32_bf16 v[26:29], v[188:191], v[204:207], v[26:29]
	v_mfma_f32_16x16x32_bf16 v[22:25], v[180:183], v[212:215], v[22:25]
	v_mfma_f32_16x16x32_bf16 v[18:21], v[188:191], v[212:215], v[18:21]
	v_mfma_f32_16x16x32_bf16 v[14:17], v[180:183], v[220:223], v[14:17]
	v_mfma_f32_16x16x32_bf16 v[10:13], v[188:191], v[220:223], v[10:13]
	v_mfma_f32_16x16x32_bf16 v[6:9], v[180:183], v[228:231], v[6:9]
	v_mfma_f32_16x16x32_bf16 v[2:5], v[188:191], v[228:231], v[2:5]
	s_setprio 0
	s_barrier
	s_add_i32 s96, s96, 2
	s_add_u32 s10, s10, 0x100
	s_addc_u32 s11, s11, 0

.LBB0_464:
	s_add_u32 s12, s42, 0x10000
	s_addc_u32 s13, s43, 0
	v_bfe_u32 v18, v9, 4, 2
	s_lshl_b32 s39, s39, 5
	v_mov_b32_e32 v169, v155
	v_and_b32_e32 v13, 15, v9
	v_lshlrev_b32_e32 v19, 4, v18
	v_lshlrev_b32_e32 v9, 2, v9
	s_and_b32 s42, s39, 0x60
	s_add_i32 m0, s80, 0x18000
	v_lshl_add_u64 v[2:3], v[2:3], 0, s[34:35]
	v_lshl_add_u64 v[14:15], s[20:21], 0, v[168:169]
	v_mov_b32_e32 v167, v155
	v_lshl_or_b32 v196, s40, 6, v13
	v_lshl_or_b32 v13, v13, 6, v19
	s_lshl_b32 s40, s40, 13
	v_and_b32_e32 v9, 32, v9
	s_lshl_b32 s39, s42, 7
	s_waitcnt vmcnt(2)
	s_barrier
	global_load_lds_dwordx4 v[2:3], off
	v_lshl_add_u64 v[2:3], v[4:5], 0, s[34:35]
	s_add_i32 m0, s80, 0x1a000
	s_add_i32 s84, s80, 0x8000
	s_add_i32 s85, s80, 0xa000
	v_lshl_add_u64 v[16:17], s[20:21], 0, v[166:167]
	v_bitop3_b32 v19, v13, s40, v9 bitop3:0xde
	global_load_lds_dwordx4 v[2:3], off
	v_lshl_add_u64 v[2:3], v[14:15], 0, s[34:35]
	s_mov_b32 m0, s84
	s_add_u32 s40, s10, 0x80080
	global_load_lds_dwordx4 v[2:3], off
	v_lshl_add_u64 v[2:3], v[16:17], 0, s[34:35]
	s_mov_b32 m0, s85
	s_addc_u32 s41, s11, 0
	global_load_lds_dwordx4 v[2:3], off
	s_add_i32 m0, s80, 0x1c000
	v_lshl_add_u64 v[2:3], s[40:41], 0, v[154:155]
	global_load_lds_dwordx4 v[2:3], off
	v_lshl_add_u64 v[2:3], s[40:41], 0, v[164:165]
	s_add_i32 m0, s80, 0x1e000
	s_cmpk_lt_u32 s38, 0x100
	global_load_lds_dwordx4 v[2:3], off
	v_lshlrev_b32_e32 v2, 15, v11
	v_and_b32_e32 v2, 0xffff0000, v2
	v_lshl_add_u32 v2, v10, 12, v2
	v_and_b32_e32 v3, 1, v11
	v_lshl_or_b32 v2, v3, 6, v2
	v_lshl_add_u32 v170, v12, 1, v2
	v_lshlrev_b32_e32 v2, 15, v6
	v_and_b32_e32 v2, 0xffff0000, v2
	v_lshl_add_u32 v2, v7, 12, v2
	v_and_b32_e32 v3, 1, v6
	s_waitcnt vmcnt(6)
	v_lshl_or_b32 v2, v3, 6, v2
	v_lshl_add_u32 v172, v8, 1, v2
	v_mov_b32_e32 v2, 0
	v_readlane_b32 s40, v241, 22
	v_bitop3_b32 v197, v13, s39, v9 bitop3:0xde
	s_cselect_b64 s[46:47], -1, 0
	s_mov_b32 s91, 0
	v_cmp_eq_u32_e64 s[38:39], 0, v18
	v_lshl_or_b32 v199, v18, 3, s42
	v_mov_b32_e32 v171, v155
	v_mov_b32_e32 v173, v155
	v_add_u32_e32 v200, 0, v19
	v_readlane_b32 s86, v241, 17
	s_mov_b32 s87, s40
	s_mov_b64 s[56:57], s[20:21]
	s_nop 0
	s_barrier
	v_readlane_b32 s41, v241, 23
	s_branch .LBB0_466
.LBB0_465:
	v_mov_b32_e32 v2, 0
	s_mov_b32 s86, s52
	s_mov_b32 s87, s54
	s_nop 0
	s_mov_b64 s[56:57], s[62:63]
	s_mov_b32 s91, s92
	s_andn2_b64 vcc, exec, s[40:41]
	s_mov_b64 s[10:11], s[60:61]
	s_cbranch_vccz .LBB0_496

.LBB0_472:
	s_add_u32 s93, s10, 0x100
	s_addc_u32 s94, s11, 0
	s_add_i32 s54, s54, s89
	s_ashr_i32 s55, s54, 31
	s_lshl_b64 s[60:61], s[54:55], 20
	s_add_u32 s62, s72, s60
	s_addc_u32 s63, s73, s61
	s_and_b64 s[60:61], s[42:43], exec
	s_cselect_b32 s55, s63, s57
	s_cselect_b32 s95, s62, s56
	s_ashr_i32 s53, s52, 31
	s_lshl_b64 s[60:61], s[52:53], 20
	s_add_u32 s60, s28, s60
	s_addc_u32 s61, s29, s61
	s_and_b64 s[64:65], s[42:43], exec
	s_cselect_b32 s53, s61, s11
	s_cselect_b32 s96, s60, s10
	s_add_u32 s10, s56, 0x80080
	s_addc_u32 s11, s57, 0
	s_waitcnt lgkmcnt(0)
	v_lshl_add_u64 v[130:131], s[10:11], 0, v[170:171]
	v_lshl_add_u64 v[132:133], s[10:11], 0, v[172:173]
	s_mov_b32 s97, -2
	s_mov_b64 s[10:11], 0
	s_add_u32 s64, s56, s10
	s_addc_u32 s65, s57, s11
	s_add_u32 s64, s64, 0x100
	s_addc_u32 s65, s65, 0
	s_add_u32 vcc_lo, s93, s10
	s_addc_u32 vcc_hi, s94, s11
	s_add_i32 s16, 0, 0x10000
	s_cmpk_eq_i32 s10, 0xf00
	s_cselect_b32 s67, s55, s65
	s_cselect_b32 s66, s95, s64
	s_cselect_b32 s65, s53, vcc_hi
	s_cselect_b32 s64, s96, vcc_lo
	s_add_i32 s24, 0, 0x14000
	v_add_u32_e32 v146, s16, v197
	v_add_u32_e32 v182, s24, v197
	ds_read_b128 v[134:137], v146
	ds_read_b128 v[138:141], v146 offset:1024
	ds_read_b128 v[142:145], v146 offset:2048
	ds_read_b128 v[146:149], v146 offset:3072
	ds_read_b128 v[150:153], v182
	ds_read_b128 v[174:177], v182 offset:1024
	ds_read_b128 v[178:181], v182 offset:2048
	ds_read_b128 v[182:185], v182 offset:3072
	v_lshl_add_u64 v[190:191], v[130:131], 0, s[10:11]
	s_add_i32 m0, s80, 0xc000
	ds_read_b128 v[186:189], v200
	ds_read_b128 v[202:205], v200 offset:1024
	ds_read_b128 v[206:209], v200 offset:2048
	ds_read_b128 v[210:213], v200 offset:3072
	ds_read_b128 v[214:217], v200 offset:4096
	ds_read_b128 v[218:221], v200 offset:5120
	ds_read_b128 v[222:225], v200 offset:6144
	ds_read_b128 v[226:229], v200 offset:7168
	global_load_lds_dwordx4 v[190:191], off
	v_lshl_add_u64 v[190:191], v[132:133], 0, s[10:11]
	s_add_i32 m0, s80, 0xe000
	s_nop 0
	global_load_lds_dwordx4 v[190:191], off
	s_waitcnt vmcnt(8)
	s_waitcnt lgkmcnt(0)
	s_barrier
	s_setprio 1
	s_waitcnt lgkmcnt(0)
	v_mfma_f32_16x16x32_bf16 v[126:129], v[134:137], v[186:189], 0
	v_mfma_f32_16x16x32_bf16 v[122:125], v[142:145], v[186:189], 0
	v_mfma_f32_16x16x32_bf16 v[118:121], v[134:137], v[206:209], 0
	v_mfma_f32_16x16x32_bf16 v[114:117], v[142:145], v[206:209], 0
	v_mfma_f32_16x16x32_bf16 v[110:113], v[134:137], v[214:217], 0
	v_mfma_f32_16x16x32_bf16 v[106:109], v[142:145], v[214:217], 0
	v_mfma_f32_16x16x32_bf16 v[102:105], v[134:137], v[222:225], 0
	v_mfma_f32_16x16x32_bf16 v[98:101], v[142:145], v[222:225], 0
	v_mfma_f32_16x16x32_bf16 v[126:129], v[138:141], v[202:205], v[126:129]
	v_mfma_f32_16x16x32_bf16 v[122:125], v[146:149], v[202:205], v[122:125]
	v_mfma_f32_16x16x32_bf16 v[118:121], v[138:141], v[210:213], v[118:121]
	v_mfma_f32_16x16x32_bf16 v[114:117], v[146:149], v[210:213], v[114:117]
	v_mfma_f32_16x16x32_bf16 v[110:113], v[138:141], v[218:221], v[110:113]
	v_mfma_f32_16x16x32_bf16 v[106:109], v[146:149], v[218:221], v[106:109]
	v_mfma_f32_16x16x32_bf16 v[102:105], v[138:141], v[226:229], v[102:105]
	v_mfma_f32_16x16x32_bf16 v[98:101], v[146:149], v[226:229], v[98:101]
	s_setprio 0
	s_setprio 1
	v_mfma_f32_16x16x32_bf16 v[94:97], v[150:153], v[186:189], 0
	v_mfma_f32_16x16x32_bf16 v[90:93], v[178:181], v[186:189], 0
	v_mfma_f32_16x16x32_bf16 v[86:89], v[150:153], v[206:209], 0
	v_mfma_f32_16x16x32_bf16 v[82:85], v[178:181], v[206:209], 0
	v_mfma_f32_16x16x32_bf16 v[78:81], v[150:153], v[214:217], 0
	v_mfma_f32_16x16x32_bf16 v[74:77], v[178:181], v[214:217], 0
	v_mfma_f32_16x16x32_bf16 v[70:73], v[150:153], v[222:225], 0
	v_mfma_f32_16x16x32_bf16 v[66:69], v[178:181], v[222:225], 0
	v_mfma_f32_16x16x32_bf16 v[94:97], v[174:177], v[202:205], v[94:97]
	v_mfma_f32_16x16x32_bf16 v[90:93], v[182:185], v[202:205], v[90:93]
	v_mfma_f32_16x16x32_bf16 v[86:89], v[174:177], v[210:213], v[86:89]
	v_mfma_f32_16x16x32_bf16 v[82:85], v[182:185], v[210:213], v[82:85]
	v_mfma_f32_16x16x32_bf16 v[78:81], v[174:177], v[218:221], v[78:81]
	v_mfma_f32_16x16x32_bf16 v[74:77], v[182:185], v[218:221], v[74:77]
	v_mfma_f32_16x16x32_bf16 v[70:73], v[174:177], v[226:229], v[70:73]
	v_mfma_f32_16x16x32_bf16 v[66:69], v[182:185], v[226:229], v[66:69]
	s_setprio 0
	s_barrier
	s_add_i32 s16, s16, s30
	v_lshl_add_u64 v[190:191], s[64:65], 0, v[154:155]
	s_mov_b32 m0, s16
	ds_read_b128 v[186:189], v200 offset:16384
	ds_read_b128 v[202:205], v200 offset:17408
	ds_read_b128 v[206:209], v200 offset:18432
	ds_read_b128 v[210:213], v200 offset:19456
	ds_read_b128 v[214:217], v200 offset:20480
	ds_read_b128 v[218:221], v200 offset:21504
	ds_read_b128 v[222:225], v200 offset:22528
	ds_read_b128 v[226:229], v200 offset:23552
	global_load_lds_dwordx4 v[190:191], off
	s_add_i32 m0, s16, 0x2000
	s_add_u32 vcc_lo, s64, 0x80000
	v_lshl_add_u64 v[230:231], s[64:65], 0, v[164:165]
	s_addc_u32 vcc_hi, s65, 0
	s_add_i32 s16, s24, s30
	global_load_lds_dwordx4 v[230:231], off
	v_lshl_add_u64 v[232:233], vcc, 0, v[154:155]
	s_mov_b32 m0, s16
	v_lshl_add_u64 v[234:235], s[66:67], 0, v[166:167]
	global_load_lds_dwordx4 v[232:233], off
	v_lshl_add_u64 v[232:233], vcc, 0, v[164:165]
	s_add_i32 m0, s16, 0x2000
	s_nop 0
	global_load_lds_dwordx4 v[232:233], off
	v_lshl_add_u64 v[232:233], s[66:67], 0, v[168:169]
	s_mov_b32 m0, s80
	s_nop 0
	global_load_lds_dwordx4 v[232:233], off
	s_mov_b32 m0, s81
	s_nop 0
	global_load_lds_dwordx4 v[234:235], off
	s_waitcnt vmcnt(8)
	s_waitcnt lgkmcnt(0)
	s_barrier
	s_setprio 1
	s_waitcnt lgkmcnt(0)
	v_mfma_f32_16x16x32_bf16 v[62:65], v[134:137], v[186:189], 0
	v_mfma_f32_16x16x32_bf16 v[58:61], v[142:145], v[186:189], 0
	v_mfma_f32_16x16x32_bf16 v[54:57], v[134:137], v[206:209], 0
	v_mfma_f32_16x16x32_bf16 v[50:53], v[142:145], v[206:209], 0
	v_mfma_f32_16x16x32_bf16 v[46:49], v[134:137], v[214:217], 0
	v_mfma_f32_16x16x32_bf16 v[42:45], v[142:145], v[214:217], 0
	v_mfma_f32_16x16x32_bf16 v[38:41], v[134:137], v[222:225], 0
	v_mfma_f32_16x16x32_bf16 v[34:37], v[142:145], v[222:225], 0
	v_mfma_f32_16x16x32_bf16 v[62:65], v[138:141], v[202:205], v[62:65]
	v_mfma_f32_16x16x32_bf16 v[58:61], v[146:149], v[202:205], v[58:61]
	v_mfma_f32_16x16x32_bf16 v[54:57], v[138:141], v[210:213], v[54:57]
	v_mfma_f32_16x16x32_bf16 v[50:53], v[146:149], v[210:213], v[50:53]
	v_mfma_f32_16x16x32_bf16 v[46:49], v[138:141], v[218:221], v[46:49]
	v_mfma_f32_16x16x32_bf16 v[42:45], v[146:149], v[218:221], v[42:45]
	v_mfma_f32_16x16x32_bf16 v[38:41], v[138:141], v[226:229], v[38:41]
	v_mfma_f32_16x16x32_bf16 v[34:37], v[146:149], v[226:229], v[34:37]
	s_setprio 0
	s_setprio 1
	v_mfma_f32_16x16x32_bf16 v[30:33], v[150:153], v[186:189], 0
	v_mfma_f32_16x16x32_bf16 v[26:29], v[178:181], v[186:189], 0
	v_mfma_f32_16x16x32_bf16 v[22:25], v[150:153], v[206:209], 0
	v_mfma_f32_16x16x32_bf16 v[18:21], v[178:181], v[206:209], 0
	v_mfma_f32_16x16x32_bf16 v[14:17], v[150:153], v[214:217], 0
	v_mfma_f32_16x16x32_bf16 v[10:13], v[178:181], v[214:217], 0
	v_mfma_f32_16x16x32_bf16 v[6:9], v[150:153], v[222:225], 0
	v_mfma_f32_16x16x32_bf16 v[2:5], v[178:181], v[222:225], 0
	v_mfma_f32_16x16x32_bf16 v[30:33], v[174:177], v[202:205], v[30:33]
	v_mfma_f32_16x16x32_bf16 v[26:29], v[182:185], v[202:205], v[26:29]
	v_mfma_f32_16x16x32_bf16 v[22:25], v[174:177], v[210:213], v[22:25]
	v_mfma_f32_16x16x32_bf16 v[18:21], v[182:185], v[210:213], v[18:21]
	v_mfma_f32_16x16x32_bf16 v[14:17], v[174:177], v[218:221], v[14:17]
	v_mfma_f32_16x16x32_bf16 v[10:13], v[182:185], v[218:221], v[10:13]
	v_mfma_f32_16x16x32_bf16 v[6:9], v[174:177], v[226:229], v[6:9]
	v_mfma_f32_16x16x32_bf16 v[2:5], v[182:185], v[226:229], v[2:5]
	s_setprio 0
	s_barrier
	s_add_i32 s16, 0, 0x18000
	s_add_i32 s24, 0, 0x1c000
	v_add_u32_e32 v146, s16, v197
	v_add_u32_e32 v182, s24, v197
	ds_read_b128 v[134:137], v146
	ds_read_b128 v[138:141], v146 offset:1024
	ds_read_b128 v[142:145], v146 offset:2048
	ds_read_b128 v[146:149], v146 offset:3072
	ds_read_b128 v[150:153], v182
	ds_read_b128 v[174:177], v182 offset:1024
	ds_read_b128 v[178:181], v182 offset:2048
	ds_read_b128 v[182:185], v182 offset:3072
	s_add_u32 s66, s66, 0x80000
	s_addc_u32 s67, s67, 0
	s_mov_b32 m0, s82
	v_lshl_add_u64 v[236:237], s[66:67], 0, v[168:169]
	ds_read_b128 v[186:189], v200 offset:32768
	ds_read_b128 v[202:205], v200 offset:33792
	ds_read_b128 v[206:209], v200 offset:34816
	ds_read_b128 v[210:213], v200 offset:35840
	ds_read_b128 v[214:217], v200 offset:36864
	ds_read_b128 v[218:221], v200 offset:37888
	ds_read_b128 v[222:225], v200 offset:38912
	ds_read_b128 v[226:229], v200 offset:39936
	global_load_lds_dwordx4 v[236:237], off
	v_lshl_add_u64 v[236:237], s[66:67], 0, v[166:167]
	s_mov_b32 m0, s83
	s_nop 0
	global_load_lds_dwordx4 v[236:237], off
	s_waitcnt vmcnt(8)
	s_waitcnt lgkmcnt(0)
	s_barrier
	s_setprio 1
	s_waitcnt lgkmcnt(0)
	v_mfma_f32_16x16x32_bf16 v[126:129], v[134:137], v[186:189], v[126:129]
	v_mfma_f32_16x16x32_bf16 v[122:125], v[142:145], v[186:189], v[122:125]
	v_mfma_f32_16x16x32_bf16 v[118:121], v[134:137], v[206:209], v[118:121]
	v_mfma_f32_16x16x32_bf16 v[114:117], v[142:145], v[206:209], v[114:117]
	v_mfma_f32_16x16x32_bf16 v[110:113], v[134:137], v[214:217], v[110:113]
	v_mfma_f32_16x16x32_bf16 v[106:109], v[142:145], v[214:217], v[106:109]
	v_mfma_f32_16x16x32_bf16 v[102:105], v[134:137], v[222:225], v[102:105]
	v_mfma_f32_16x16x32_bf16 v[98:101], v[142:145], v[222:225], v[98:101]
	v_mfma_f32_16x16x32_bf16 v[126:129], v[138:141], v[202:205], v[126:129]
	v_mfma_f32_16x16x32_bf16 v[122:125], v[146:149], v[202:205], v[122:125]
	v_mfma_f32_16x16x32_bf16 v[118:121], v[138:141], v[210:213], v[118:121]
	v_mfma_f32_16x16x32_bf16 v[114:117], v[146:149], v[210:213], v[114:117]
	v_mfma_f32_16x16x32_bf16 v[110:113], v[138:141], v[218:221], v[110:113]
	v_mfma_f32_16x16x32_bf16 v[106:109], v[146:149], v[218:221], v[106:109]
	v_mfma_f32_16x16x32_bf16 v[102:105], v[138:141], v[226:229], v[102:105]
	v_mfma_f32_16x16x32_bf16 v[98:101], v[146:149], v[226:229], v[98:101]
	s_setprio 0
	s_setprio 1
	v_mfma_f32_16x16x32_bf16 v[94:97], v[150:153], v[186:189], v[94:97]
	v_mfma_f32_16x16x32_bf16 v[90:93], v[178:181], v[186:189], v[90:93]
	v_mfma_f32_16x16x32_bf16 v[86:89], v[150:153], v[206:209], v[86:89]
	v_mfma_f32_16x16x32_bf16 v[82:85], v[178:181], v[206:209], v[82:85]
	v_mfma_f32_16x16x32_bf16 v[78:81], v[150:153], v[214:217], v[78:81]
	v_mfma_f32_16x16x32_bf16 v[74:77], v[178:181], v[214:217], v[74:77]
	v_mfma_f32_16x16x32_bf16 v[70:73], v[150:153], v[222:225], v[70:73]
	v_mfma_f32_16x16x32_bf16 v[66:69], v[178:181], v[222:225], v[66:69]
	v_mfma_f32_16x16x32_bf16 v[94:97], v[174:177], v[202:205], v[94:97]
	v_mfma_f32_16x16x32_bf16 v[90:93], v[182:185], v[202:205], v[90:93]
	v_mfma_f32_16x16x32_bf16 v[86:89], v[174:177], v[210:213], v[86:89]
	v_mfma_f32_16x16x32_bf16 v[82:85], v[182:185], v[210:213], v[82:85]
	v_mfma_f32_16x16x32_bf16 v[78:81], v[174:177], v[218:221], v[78:81]
	v_mfma_f32_16x16x32_bf16 v[74:77], v[182:185], v[218:221], v[74:77]
	v_mfma_f32_16x16x32_bf16 v[70:73], v[174:177], v[226:229], v[70:73]
	v_mfma_f32_16x16x32_bf16 v[66:69], v[182:185], v[226:229], v[66:69]
	s_setprio 0
	s_barrier
	s_add_i32 s16, s16, s30
	v_lshl_add_u64 v[190:191], v[190:191], 0, s[34:35]
	s_mov_b32 m0, s16
	ds_read_b128 v[186:189], v200 offset:49152
	ds_read_b128 v[202:205], v200 offset:50176
	ds_read_b128 v[206:209], v200 offset:51200
	ds_read_b128 v[210:213], v200 offset:52224
	ds_read_b128 v[214:217], v200 offset:53248
	ds_read_b128 v[218:221], v200 offset:54272
	ds_read_b128 v[222:225], v200 offset:55296
	ds_read_b128 v[226:229], v200 offset:56320
	global_load_lds_dwordx4 v[190:191], off
	s_add_i32 m0, s16, 0x2000
	s_add_u32 s64, s64, 0x80080
	v_lshl_add_u64 v[190:191], v[230:231], 0, s[34:35]
	s_addc_u32 s65, s65, 0
	s_add_i32 s16, s24, s30
	global_load_lds_dwordx4 v[190:191], off
	v_lshl_add_u64 v[190:191], s[64:65], 0, v[154:155]
	s_mov_b32 m0, s16
	s_nop 0
	global_load_lds_dwordx4 v[190:191], off
	v_lshl_add_u64 v[190:191], s[64:65], 0, v[164:165]
	s_add_i32 m0, s16, 0x2000
	s_nop 0
	global_load_lds_dwordx4 v[190:191], off
	v_lshl_add_u64 v[190:191], v[232:233], 0, s[34:35]
	s_mov_b32 m0, s84
	s_nop 0
	global_load_lds_dwordx4 v[190:191], off
	v_lshl_add_u64 v[190:191], v[234:235], 0, s[34:35]
	s_mov_b32 m0, s85
	s_nop 0
	global_load_lds_dwordx4 v[190:191], off
	s_waitcnt vmcnt(8)
	s_waitcnt lgkmcnt(0)
	s_barrier
	s_setprio 1
	s_waitcnt lgkmcnt(0)
	v_mfma_f32_16x16x32_bf16 v[62:65], v[134:137], v[186:189], v[62:65]
	v_mfma_f32_16x16x32_bf16 v[58:61], v[142:145], v[186:189], v[58:61]
	v_mfma_f32_16x16x32_bf16 v[54:57], v[134:137], v[206:209], v[54:57]
	v_mfma_f32_16x16x32_bf16 v[50:53], v[142:145], v[206:209], v[50:53]
	v_mfma_f32_16x16x32_bf16 v[46:49], v[134:137], v[214:217], v[46:49]
	v_mfma_f32_16x16x32_bf16 v[42:45], v[142:145], v[214:217], v[42:45]
	v_mfma_f32_16x16x32_bf16 v[38:41], v[134:137], v[222:225], v[38:41]
	v_mfma_f32_16x16x32_bf16 v[34:37], v[142:145], v[222:225], v[34:37]
	v_mfma_f32_16x16x32_bf16 v[62:65], v[138:141], v[202:205], v[62:65]
	v_mfma_f32_16x16x32_bf16 v[58:61], v[146:149], v[202:205], v[58:61]
	v_mfma_f32_16x16x32_bf16 v[54:57], v[138:141], v[210:213], v[54:57]
	v_mfma_f32_16x16x32_bf16 v[50:53], v[146:149], v[210:213], v[50:53]
	v_mfma_f32_16x16x32_bf16 v[46:49], v[138:141], v[218:221], v[46:49]
	v_mfma_f32_16x16x32_bf16 v[42:45], v[146:149], v[218:221], v[42:45]
	v_mfma_f32_16x16x32_bf16 v[38:41], v[138:141], v[226:229], v[38:41]
	v_mfma_f32_16x16x32_bf16 v[34:37], v[146:149], v[226:229], v[34:37]
	s_setprio 0
	s_setprio 1
	v_mfma_f32_16x16x32_bf16 v[30:33], v[150:153], v[186:189], v[30:33]
	v_mfma_f32_16x16x32_bf16 v[26:29], v[178:181], v[186:189], v[26:29]
	v_mfma_f32_16x16x32_bf16 v[22:25], v[150:153], v[206:209], v[22:25]
	v_mfma_f32_16x16x32_bf16 v[18:21], v[178:181], v[206:209], v[18:21]
	v_mfma_f32_16x16x32_bf16 v[14:17], v[150:153], v[214:217], v[14:17]
	v_mfma_f32_16x16x32_bf16 v[10:13], v[178:181], v[214:217], v[10:13]
	v_mfma_f32_16x16x32_bf16 v[6:9], v[150:153], v[222:225], v[6:9]
	v_mfma_f32_16x16x32_bf16 v[2:5], v[178:181], v[222:225], v[2:5]
	v_mfma_f32_16x16x32_bf16 v[30:33], v[174:177], v[202:205], v[30:33]
	v_mfma_f32_16x16x32_bf16 v[26:29], v[182:185], v[202:205], v[26:29]
	v_mfma_f32_16x16x32_bf16 v[22:25], v[174:177], v[210:213], v[22:25]
	v_mfma_f32_16x16x32_bf16 v[18:21], v[182:185], v[210:213], v[18:21]
	v_mfma_f32_16x16x32_bf16 v[14:17], v[174:177], v[218:221], v[14:17]
	v_mfma_f32_16x16x32_bf16 v[10:13], v[182:185], v[218:221], v[10:13]
	v_mfma_f32_16x16x32_bf16 v[6:9], v[174:177], v[226:229], v[6:9]
	v_mfma_f32_16x16x32_bf16 v[2:5], v[182:185], v[226:229], v[2:5]
	s_setprio 0
	s_barrier
	s_add_i32 s97, s97, 2
	s_add_u32 s10, s10, 0x100
	s_addc_u32 s11, s11, 0

.LBB0_595:
	v_readlane_b32 s10, v242, 13
	s_add_u32 s48, s10, 0x20000
	v_readlane_b32 s10, v240, 10
	s_waitcnt vmcnt(0)
	v_lshrrev_b32_e32 v19, 1, v2
	s_addc_u32 s49, s10, 0
	v_and_b32_e32 v19, 24, v19
	s_and_b64 s[10:11], s[34:35], exec
	v_and_b32_e32 v18, 15, v2
	v_lshlrev_b32_e32 v20, 1, v19
	v_lshlrev_b32_e32 v2, 2, v2
	s_cselect_b32 s37, 16, 0
	s_and_b32 s10, s8, 3
	v_lshl_or_b32 v177, s9, 6, v18
	v_lshl_or_b32 v18, v18, 6, v20
	s_lshl_b32 s9, s9, 13
	v_and_b32_e32 v2, 32, v2
	s_add_i32 m0, s25, 0x18000
	v_lshl_add_u64 v[10:11], v[10:11], 0, s[28:29]
	v_bitop3_b32 v20, v18, s9, v2 bitop3:0xde
	s_lshl_b32 s9, s10, 5
	s_lshl_b32 s10, s10, 12
	s_waitcnt vmcnt(2)
	s_barrier
	global_load_lds_dwordx4 v[10:11], off
	v_lshl_add_u64 v[8:9], v[8:9], 0, s[28:29]
	s_add_i32 m0, s25, 0x1a000
	s_add_i32 s45, s25, 0x8000
	s_add_i32 s60, s25, 0xa000
	v_bitop3_b32 v204, v18, s10, v2 bitop3:0xde
	global_load_lds_dwordx4 v[8:9], off
	v_lshl_add_u64 v[4:5], v[4:5], 0, s[28:29]
	s_mov_b32 m0, s45
	s_add_u32 s10, s0, 0x80080
	global_load_lds_dwordx4 v[4:5], off
	v_lshl_add_u64 v[4:5], v[6:7], 0, s[28:29]
	s_mov_b32 m0, s60
	s_addc_u32 s11, s1, 0
	global_load_lds_dwordx4 v[4:5], off
	s_add_i32 m0, s25, 0x1c000
	v_lshl_add_u64 v[4:5], s[10:11], 0, v[170:171]
	global_load_lds_dwordx4 v[4:5], off
	v_lshl_add_u64 v[4:5], s[10:11], 0, v[174:175]
	s_add_i32 m0, s25, 0x1e000
	s_cmpk_lt_u32 s13, 0x100
	global_load_lds_dwordx4 v[4:5], off
	s_cselect_b64 s[50:51], -1, 0
	s_lshl_b32 s61, s12, 3
	v_cvt_f32_u32_e32 v2, s61
	v_or_b32_e32 v176, s9, v19
	v_bitop3_b32 v6, s9, 56, v19 bitop3:0xc8
	s_bfe_u32 s62, s8, 0x10001
	v_rcp_iflag_f32_e32 v4, v2
	v_readlane_b32 s8, v241, 38
	v_lshlrev_b32_e32 v2, 2, v6
	v_readlane_b32 s9, v241, 39
	v_mul_f32_e32 v4, 0x4f7ffffe, v4
	v_cvt_u32_f32_e32 v4, v4
	v_lshl_add_u64 v[178:179], s[8:9], 0, v[2:3]
	v_readlane_b32 s8, v241, 40
	v_readlane_b32 s9, v241, 41
	s_waitcnt vmcnt(6)
	s_mov_b32 s74, 0
	s_lshl_b32 s63, s12, 2
	v_lshl_add_u64 v[180:181], s[8:9], 0, v[2:3]
	v_lshlrev_b32_e32 v2, 15, v12
	v_and_b32_e32 v2, 0xffff0000, v2
	v_readfirstlane_b32 s9, v4
	v_lshl_add_u32 v2, v13, 12, v2
	v_and_b32_e32 v4, 1, v12
	v_lshl_or_b32 v2, v4, 6, v2
	v_lshl_add_u32 v182, v14, 1, v2
	v_lshlrev_b32_e32 v2, 15, v15
	s_sub_i32 s8, 0, s61
	v_and_b32_e32 v2, 0xffff0000, v2
	s_mul_i32 s8, s8, s9
	v_lshl_add_u32 v2, v16, 12, v2
	v_and_b32_e32 v4, 1, v15
	s_mul_hi_u32 s8, s9, s8
	v_lshl_or_b32 v2, v4, 6, v2
	v_mov_b32_e32 v4, 0
	s_add_i32 s67, s9, s8
	v_mov_b32_e32 v183, v3
	v_lshl_add_u32 v184, v17, 1, v2
	v_mov_b32_e32 v185, v3
	v_add_u32_e32 v205, 0, v20
	v_lshlrev_b32_e32 v2, 1, v6
	s_nop 0
	s_barrier
	s_branch .LBB0_597
.LBB0_596:
	v_mov_b32_e32 v4, 0
	s_mov_b32 s66, s42
	s_mov_b32 s44, s54
	s_nop 0
	s_mov_b64 s[52:53], s[56:57]
	s_mov_b32 s74, s75
	s_andn2_b64 vcc, exec, s[38:39]
	s_mov_b64 s[0:1], s[34:35]
	s_cbranch_vccz .LBB0_650

.LBB0_622:
	s_add_i32 s54, s54, s89
	s_add_u32 s76, s0, 0x100
	s_addc_u32 s77, s1, 0
	s_ashr_i32 s55, s54, 31
	s_lshl_b64 s[8:9], s[54:55], 20
	s_add_u32 s56, s22, s8
	s_addc_u32 s57, s23, s9
	s_and_b64 s[8:9], s[40:41], exec
	s_cselect_b32 s12, s57, s53
	s_cselect_b32 s13, s56, s52
	s_ashr_i32 s43, s42, 31
	s_lshl_b64 s[8:9], s[42:43], 20
	s_add_u32 s34, s15, s8
	s_addc_u32 s35, s14, s9
	s_and_b64 s[8:9], s[40:41], exec
	s_cselect_b32 s26, s35, s1
	s_cselect_b32 s27, s34, s0
	s_add_u32 s0, s52, 0x80080
	s_addc_u32 s1, s53, 0
	v_lshl_add_u64 v[132:133], s[0:1], 0, v[182:183]
	v_lshl_add_u64 v[134:135], s[0:1], 0, v[184:185]
	s_mov_b32 s43, -2
	s_mov_b64 s[0:1], 0
	s_add_u32 s8, s52, s0
	s_addc_u32 s9, s53, s1
	s_add_u32 s8, s8, 0x100
	s_addc_u32 s9, s9, 0
	s_add_u32 s55, s76, s0
	s_addc_u32 s78, s77, s1
	s_add_i32 s79, 0, 0x10000
	s_cmpk_eq_i32 s0, 0xf00
	s_cselect_b32 s11, s12, s9
	s_cselect_b32 s10, s13, s8
	s_cselect_b32 s9, s26, s78
	s_cselect_b32 s8, s27, s55
	s_add_i32 s55, 0, 0x14000
	v_add_u32_e32 v148, s79, v204
	v_add_u32_e32 v186, s55, v204
	ds_read_b128 v[136:139], v148
	ds_read_b128 v[140:143], v148 offset:1024
	ds_read_b128 v[144:147], v148 offset:2048
	ds_read_b128 v[148:151], v148 offset:3072
	ds_read_b128 v[152:155], v186
	ds_read_b128 v[156:159], v186 offset:1024
	ds_read_b128 v[160:163], v186 offset:2048
	ds_read_b128 v[186:189], v186 offset:3072
	v_lshl_add_u64 v[230:231], v[132:133], 0, s[0:1]
	s_add_i32 m0, s25, 0xc000
	ds_read_b128 v[190:193], v205
	ds_read_b128 v[194:197], v205 offset:1024
	ds_read_b128 v[206:209], v205 offset:2048
	ds_read_b128 v[210:213], v205 offset:3072
	ds_read_b128 v[214:217], v205 offset:4096
	ds_read_b128 v[218:221], v205 offset:5120
	ds_read_b128 v[222:225], v205 offset:6144
	ds_read_b128 v[226:229], v205 offset:7168
	global_load_lds_dwordx4 v[230:231], off
	v_lshl_add_u64 v[230:231], v[134:135], 0, s[0:1]
	s_add_i32 m0, s25, 0xe000
	s_nop 0
	global_load_lds_dwordx4 v[230:231], off
	s_waitcnt vmcnt(8)
	s_waitcnt lgkmcnt(0)
	s_barrier
	s_setprio 1
	s_waitcnt lgkmcnt(0)
	v_mfma_f32_16x16x32_bf16 v[128:131], v[136:139], v[190:193], 0
	v_mfma_f32_16x16x32_bf16 v[124:127], v[144:147], v[190:193], 0
	v_mfma_f32_16x16x32_bf16 v[120:123], v[136:139], v[206:209], 0
	v_mfma_f32_16x16x32_bf16 v[116:119], v[144:147], v[206:209], 0
	v_mfma_f32_16x16x32_bf16 v[112:115], v[136:139], v[214:217], 0
	v_mfma_f32_16x16x32_bf16 v[108:111], v[144:147], v[214:217], 0
	v_mfma_f32_16x16x32_bf16 v[104:107], v[136:139], v[222:225], 0
	v_mfma_f32_16x16x32_bf16 v[100:103], v[144:147], v[222:225], 0
	v_mfma_f32_16x16x32_bf16 v[128:131], v[140:143], v[194:197], v[128:131]
	v_mfma_f32_16x16x32_bf16 v[124:127], v[148:151], v[194:197], v[124:127]
	v_mfma_f32_16x16x32_bf16 v[120:123], v[140:143], v[210:213], v[120:123]
	v_mfma_f32_16x16x32_bf16 v[116:119], v[148:151], v[210:213], v[116:119]
	v_mfma_f32_16x16x32_bf16 v[112:115], v[140:143], v[218:221], v[112:115]
	v_mfma_f32_16x16x32_bf16 v[108:111], v[148:151], v[218:221], v[108:111]
	v_mfma_f32_16x16x32_bf16 v[104:107], v[140:143], v[226:229], v[104:107]
	v_mfma_f32_16x16x32_bf16 v[100:103], v[148:151], v[226:229], v[100:103]
	s_setprio 0
	s_setprio 1
	v_mfma_f32_16x16x32_bf16 v[96:99], v[152:155], v[190:193], 0
	v_mfma_f32_16x16x32_bf16 v[92:95], v[160:163], v[190:193], 0
	v_mfma_f32_16x16x32_bf16 v[88:91], v[152:155], v[206:209], 0
	v_mfma_f32_16x16x32_bf16 v[84:87], v[160:163], v[206:209], 0
	v_mfma_f32_16x16x32_bf16 v[80:83], v[152:155], v[214:217], 0
	v_mfma_f32_16x16x32_bf16 v[76:79], v[160:163], v[214:217], 0
	v_mfma_f32_16x16x32_bf16 v[72:75], v[152:155], v[222:225], 0
	v_mfma_f32_16x16x32_bf16 v[68:71], v[160:163], v[222:225], 0
	v_mfma_f32_16x16x32_bf16 v[96:99], v[156:159], v[194:197], v[96:99]
	v_mfma_f32_16x16x32_bf16 v[92:95], v[186:189], v[194:197], v[92:95]
	v_mfma_f32_16x16x32_bf16 v[88:91], v[156:159], v[210:213], v[88:91]
	v_mfma_f32_16x16x32_bf16 v[84:87], v[186:189], v[210:213], v[84:87]
	v_mfma_f32_16x16x32_bf16 v[80:83], v[156:159], v[218:221], v[80:83]
	v_mfma_f32_16x16x32_bf16 v[76:79], v[186:189], v[218:221], v[76:79]
	v_mfma_f32_16x16x32_bf16 v[72:75], v[156:159], v[226:229], v[72:75]
	v_mfma_f32_16x16x32_bf16 v[68:71], v[186:189], v[226:229], v[68:71]
	s_setprio 0
	s_barrier
	s_add_i32 s78, s79, s24
	v_lshl_add_u64 v[230:231], s[8:9], 0, v[170:171]
	s_mov_b32 m0, s78
	ds_read_b128 v[190:193], v205 offset:16384
	ds_read_b128 v[194:197], v205 offset:17408
	ds_read_b128 v[206:209], v205 offset:18432
	ds_read_b128 v[210:213], v205 offset:19456
	ds_read_b128 v[214:217], v205 offset:20480
	ds_read_b128 v[218:221], v205 offset:21504
	ds_read_b128 v[222:225], v205 offset:22528
	ds_read_b128 v[226:229], v205 offset:23552
	global_load_lds_dwordx4 v[230:231], off
	s_add_i32 m0, s78, 0x2000
	s_add_u32 s78, s8, 0x80000
	v_lshl_add_u64 v[232:233], s[8:9], 0, v[174:175]
	s_addc_u32 s79, s9, 0
	s_add_i32 s55, s55, s24
	global_load_lds_dwordx4 v[232:233], off
	v_lshl_add_u64 v[234:235], s[78:79], 0, v[170:171]
	s_mov_b32 m0, s55
	v_lshl_add_u64 v[236:237], s[10:11], 0, v[172:173]
	global_load_lds_dwordx4 v[234:235], off
	v_lshl_add_u64 v[234:235], s[78:79], 0, v[174:175]
	s_add_i32 m0, s55, 0x2000
	s_nop 0
	global_load_lds_dwordx4 v[234:235], off
	v_lshl_add_u64 v[234:235], s[10:11], 0, v[168:169]
	s_mov_b32 m0, s25
	s_nop 0
	global_load_lds_dwordx4 v[234:235], off
	s_mov_b32 m0, s30
	s_nop 0
	global_load_lds_dwordx4 v[236:237], off
	s_waitcnt vmcnt(8)
	s_waitcnt lgkmcnt(0)
	s_barrier
	s_setprio 1
	s_waitcnt lgkmcnt(0)
	v_mfma_f32_16x16x32_bf16 v[64:67], v[136:139], v[190:193], 0
	v_mfma_f32_16x16x32_bf16 v[60:63], v[144:147], v[190:193], 0
	v_mfma_f32_16x16x32_bf16 v[56:59], v[136:139], v[206:209], 0
	v_mfma_f32_16x16x32_bf16 v[52:55], v[144:147], v[206:209], 0
	v_mfma_f32_16x16x32_bf16 v[48:51], v[136:139], v[214:217], 0
	v_mfma_f32_16x16x32_bf16 v[44:47], v[144:147], v[214:217], 0
	v_mfma_f32_16x16x32_bf16 v[40:43], v[136:139], v[222:225], 0
	v_mfma_f32_16x16x32_bf16 v[36:39], v[144:147], v[222:225], 0
	v_mfma_f32_16x16x32_bf16 v[64:67], v[140:143], v[194:197], v[64:67]
	v_mfma_f32_16x16x32_bf16 v[60:63], v[148:151], v[194:197], v[60:63]
	v_mfma_f32_16x16x32_bf16 v[56:59], v[140:143], v[210:213], v[56:59]
	v_mfma_f32_16x16x32_bf16 v[52:55], v[148:151], v[210:213], v[52:55]
	v_mfma_f32_16x16x32_bf16 v[48:51], v[140:143], v[218:221], v[48:51]
	v_mfma_f32_16x16x32_bf16 v[44:47], v[148:151], v[218:221], v[44:47]
	v_mfma_f32_16x16x32_bf16 v[40:43], v[140:143], v[226:229], v[40:43]
	v_mfma_f32_16x16x32_bf16 v[36:39], v[148:151], v[226:229], v[36:39]
	s_setprio 0
	s_setprio 1
	v_mfma_f32_16x16x32_bf16 v[32:35], v[152:155], v[190:193], 0
	v_mfma_f32_16x16x32_bf16 v[28:31], v[160:163], v[190:193], 0
	v_mfma_f32_16x16x32_bf16 v[24:27], v[152:155], v[206:209], 0
	v_mfma_f32_16x16x32_bf16 v[20:23], v[160:163], v[206:209], 0
	v_mfma_f32_16x16x32_bf16 v[16:19], v[152:155], v[214:217], 0
	v_mfma_f32_16x16x32_bf16 v[12:15], v[160:163], v[214:217], 0
	v_mfma_f32_16x16x32_bf16 v[8:11], v[152:155], v[222:225], 0
	v_mfma_f32_16x16x32_bf16 v[4:7], v[160:163], v[222:225], 0
	v_mfma_f32_16x16x32_bf16 v[32:35], v[156:159], v[194:197], v[32:35]
	v_mfma_f32_16x16x32_bf16 v[28:31], v[186:189], v[194:197], v[28:31]
	v_mfma_f32_16x16x32_bf16 v[24:27], v[156:159], v[210:213], v[24:27]
	v_mfma_f32_16x16x32_bf16 v[20:23], v[186:189], v[210:213], v[20:23]
	v_mfma_f32_16x16x32_bf16 v[16:19], v[156:159], v[218:221], v[16:19]
	v_mfma_f32_16x16x32_bf16 v[12:15], v[186:189], v[218:221], v[12:15]
	v_mfma_f32_16x16x32_bf16 v[8:11], v[156:159], v[226:229], v[8:11]
	v_mfma_f32_16x16x32_bf16 v[4:7], v[186:189], v[226:229], v[4:7]
	s_setprio 0
	s_barrier
	s_add_i32 s55, 0, 0x18000
	s_add_i32 s78, 0, 0x1c000
	v_add_u32_e32 v148, s55, v204
	v_add_u32_e32 v186, s78, v204
	ds_read_b128 v[136:139], v148
	ds_read_b128 v[140:143], v148 offset:1024
	ds_read_b128 v[144:147], v148 offset:2048
	ds_read_b128 v[148:151], v148 offset:3072
	ds_read_b128 v[152:155], v186
	ds_read_b128 v[156:159], v186 offset:1024
	ds_read_b128 v[160:163], v186 offset:2048
	ds_read_b128 v[186:189], v186 offset:3072
	s_add_u32 s10, s10, 0x80000
	s_addc_u32 s11, s11, 0
	s_mov_b32 m0, s31
	v_lshl_add_u64 v[238:239], s[10:11], 0, v[168:169]
	ds_read_b128 v[190:193], v205 offset:32768
	ds_read_b128 v[194:197], v205 offset:33792
	ds_read_b128 v[206:209], v205 offset:34816
	ds_read_b128 v[210:213], v205 offset:35840
	ds_read_b128 v[214:217], v205 offset:36864
	ds_read_b128 v[218:221], v205 offset:37888
	ds_read_b128 v[222:225], v205 offset:38912
	ds_read_b128 v[226:229], v205 offset:39936
	global_load_lds_dwordx4 v[238:239], off
	v_lshl_add_u64 v[238:239], s[10:11], 0, v[172:173]
	s_mov_b32 m0, s36
	s_nop 0
	global_load_lds_dwordx4 v[238:239], off
	s_waitcnt vmcnt(8)
	s_waitcnt lgkmcnt(0)
	s_barrier
	s_setprio 1
	s_waitcnt lgkmcnt(0)
	v_mfma_f32_16x16x32_bf16 v[128:131], v[136:139], v[190:193], v[128:131]
	v_mfma_f32_16x16x32_bf16 v[124:127], v[144:147], v[190:193], v[124:127]
	v_mfma_f32_16x16x32_bf16 v[120:123], v[136:139], v[206:209], v[120:123]
	v_mfma_f32_16x16x32_bf16 v[116:119], v[144:147], v[206:209], v[116:119]
	v_mfma_f32_16x16x32_bf16 v[112:115], v[136:139], v[214:217], v[112:115]
	v_mfma_f32_16x16x32_bf16 v[108:111], v[144:147], v[214:217], v[108:111]
	v_mfma_f32_16x16x32_bf16 v[104:107], v[136:139], v[222:225], v[104:107]
	v_mfma_f32_16x16x32_bf16 v[100:103], v[144:147], v[222:225], v[100:103]
	v_mfma_f32_16x16x32_bf16 v[128:131], v[140:143], v[194:197], v[128:131]
	v_mfma_f32_16x16x32_bf16 v[124:127], v[148:151], v[194:197], v[124:127]
	v_mfma_f32_16x16x32_bf16 v[120:123], v[140:143], v[210:213], v[120:123]
	v_mfma_f32_16x16x32_bf16 v[116:119], v[148:151], v[210:213], v[116:119]
	v_mfma_f32_16x16x32_bf16 v[112:115], v[140:143], v[218:221], v[112:115]
	v_mfma_f32_16x16x32_bf16 v[108:111], v[148:151], v[218:221], v[108:111]
	v_mfma_f32_16x16x32_bf16 v[104:107], v[140:143], v[226:229], v[104:107]
	v_mfma_f32_16x16x32_bf16 v[100:103], v[148:151], v[226:229], v[100:103]
	s_setprio 0
	s_setprio 1
	v_mfma_f32_16x16x32_bf16 v[96:99], v[152:155], v[190:193], v[96:99]
	v_mfma_f32_16x16x32_bf16 v[92:95], v[160:163], v[190:193], v[92:95]
	v_mfma_f32_16x16x32_bf16 v[88:91], v[152:155], v[206:209], v[88:91]
	v_mfma_f32_16x16x32_bf16 v[84:87], v[160:163], v[206:209], v[84:87]
	v_mfma_f32_16x16x32_bf16 v[80:83], v[152:155], v[214:217], v[80:83]
	v_mfma_f32_16x16x32_bf16 v[76:79], v[160:163], v[214:217], v[76:79]
	v_mfma_f32_16x16x32_bf16 v[72:75], v[152:155], v[222:225], v[72:75]
	v_mfma_f32_16x16x32_bf16 v[68:71], v[160:163], v[222:225], v[68:71]
	v_mfma_f32_16x16x32_bf16 v[96:99], v[156:159], v[194:197], v[96:99]
	v_mfma_f32_16x16x32_bf16 v[92:95], v[186:189], v[194:197], v[92:95]
	v_mfma_f32_16x16x32_bf16 v[88:91], v[156:159], v[210:213], v[88:91]
	v_mfma_f32_16x16x32_bf16 v[84:87], v[186:189], v[210:213], v[84:87]
	v_mfma_f32_16x16x32_bf16 v[80:83], v[156:159], v[218:221], v[80:83]
	v_mfma_f32_16x16x32_bf16 v[76:79], v[186:189], v[218:221], v[76:79]
	v_mfma_f32_16x16x32_bf16 v[72:75], v[156:159], v[226:229], v[72:75]
	v_mfma_f32_16x16x32_bf16 v[68:71], v[186:189], v[226:229], v[68:71]
	s_setprio 0
	s_barrier
	s_add_i32 s10, s55, s24
	v_lshl_add_u64 v[230:231], v[230:231], 0, s[28:29]
	s_mov_b32 m0, s10
	ds_read_b128 v[190:193], v205 offset:49152
	ds_read_b128 v[194:197], v205 offset:50176
	ds_read_b128 v[206:209], v205 offset:51200
	ds_read_b128 v[210:213], v205 offset:52224
	ds_read_b128 v[214:217], v205 offset:53248
	ds_read_b128 v[218:221], v205 offset:54272
	ds_read_b128 v[222:225], v205 offset:55296
	ds_read_b128 v[226:229], v205 offset:56320
	global_load_lds_dwordx4 v[230:231], off
	s_add_i32 m0, s10, 0x2000
	s_add_u32 s8, s8, 0x80080
	v_lshl_add_u64 v[230:231], v[232:233], 0, s[28:29]
	s_addc_u32 s9, s9, 0
	s_add_i32 s10, s78, s24
	global_load_lds_dwordx4 v[230:231], off
	v_lshl_add_u64 v[230:231], s[8:9], 0, v[170:171]
	s_mov_b32 m0, s10
	s_nop 0
	global_load_lds_dwordx4 v[230:231], off
	v_lshl_add_u64 v[230:231], s[8:9], 0, v[174:175]
	s_add_i32 m0, s10, 0x2000
	s_nop 0
	global_load_lds_dwordx4 v[230:231], off
	v_lshl_add_u64 v[230:231], v[234:235], 0, s[28:29]
	s_mov_b32 m0, s45
	s_nop 0
	global_load_lds_dwordx4 v[230:231], off
	v_lshl_add_u64 v[230:231], v[236:237], 0, s[28:29]
	s_mov_b32 m0, s60
	s_nop 0
	global_load_lds_dwordx4 v[230:231], off
	s_waitcnt vmcnt(8)
	s_waitcnt lgkmcnt(0)
	s_barrier
	s_setprio 1
	s_waitcnt lgkmcnt(0)
	v_mfma_f32_16x16x32_bf16 v[64:67], v[136:139], v[190:193], v[64:67]
	v_mfma_f32_16x16x32_bf16 v[60:63], v[144:147], v[190:193], v[60:63]
	v_mfma_f32_16x16x32_bf16 v[56:59], v[136:139], v[206:209], v[56:59]
	v_mfma_f32_16x16x32_bf16 v[52:55], v[144:147], v[206:209], v[52:55]
	v_mfma_f32_16x16x32_bf16 v[48:51], v[136:139], v[214:217], v[48:51]
	v_mfma_f32_16x16x32_bf16 v[44:47], v[144:147], v[214:217], v[44:47]
	v_mfma_f32_16x16x32_bf16 v[40:43], v[136:139], v[222:225], v[40:43]
	v_mfma_f32_16x16x32_bf16 v[36:39], v[144:147], v[222:225], v[36:39]
	v_mfma_f32_16x16x32_bf16 v[64:67], v[140:143], v[194:197], v[64:67]
	v_mfma_f32_16x16x32_bf16 v[60:63], v[148:151], v[194:197], v[60:63]
	v_mfma_f32_16x16x32_bf16 v[56:59], v[140:143], v[210:213], v[56:59]
	v_mfma_f32_16x16x32_bf16 v[52:55], v[148:151], v[210:213], v[52:55]
	v_mfma_f32_16x16x32_bf16 v[48:51], v[140:143], v[218:221], v[48:51]
	v_mfma_f32_16x16x32_bf16 v[44:47], v[148:151], v[218:221], v[44:47]
	v_mfma_f32_16x16x32_bf16 v[40:43], v[140:143], v[226:229], v[40:43]
	v_mfma_f32_16x16x32_bf16 v[36:39], v[148:151], v[226:229], v[36:39]
	s_setprio 0
	s_setprio 1
	v_mfma_f32_16x16x32_bf16 v[32:35], v[152:155], v[190:193], v[32:35]
	v_mfma_f32_16x16x32_bf16 v[28:31], v[160:163], v[190:193], v[28:31]
	v_mfma_f32_16x16x32_bf16 v[24:27], v[152:155], v[206:209], v[24:27]
	v_mfma_f32_16x16x32_bf16 v[20:23], v[160:163], v[206:209], v[20:23]
	v_mfma_f32_16x16x32_bf16 v[16:19], v[152:155], v[214:217], v[16:19]
	v_mfma_f32_16x16x32_bf16 v[12:15], v[160:163], v[214:217], v[12:15]
	v_mfma_f32_16x16x32_bf16 v[8:11], v[152:155], v[222:225], v[8:11]
	v_mfma_f32_16x16x32_bf16 v[4:7], v[160:163], v[222:225], v[4:7]
	v_mfma_f32_16x16x32_bf16 v[32:35], v[156:159], v[194:197], v[32:35]
	v_mfma_f32_16x16x32_bf16 v[28:31], v[186:189], v[194:197], v[28:31]
	v_mfma_f32_16x16x32_bf16 v[24:27], v[156:159], v[210:213], v[24:27]
	v_mfma_f32_16x16x32_bf16 v[20:23], v[186:189], v[210:213], v[20:23]
	v_mfma_f32_16x16x32_bf16 v[16:19], v[156:159], v[218:221], v[16:19]
	v_mfma_f32_16x16x32_bf16 v[12:15], v[186:189], v[218:221], v[12:15]
	v_mfma_f32_16x16x32_bf16 v[8:11], v[156:159], v[226:229], v[8:11]
	v_mfma_f32_16x16x32_bf16 v[4:7], v[186:189], v[226:229], v[4:7]
	s_setprio 0
	s_barrier
	s_add_i32 s43, s43, 2
	s_add_u32 s0, s0, 0x100
	s_addc_u32 s1, s1, 0

.LBB0_857:
	v_readlane_b32 s8, v242, 13
	s_add_u32 s8, s8, 0x30000
	v_readlane_b32 s9, v240, 10
	v_readlane_b32 s34, v240, 2
	s_addc_u32 s9, s9, 0
	s_waitcnt vmcnt(0)
	v_bfe_u32 v20, v11, 4, 2
	s_lshl_b32 s13, s13, 5
	v_mov_b32_e32 v161, v3
	v_readlane_b32 s35, v240, 3
	v_and_b32_e32 v15, 15, v11
	v_lshlrev_b32_e32 v21, 4, v20
	v_lshlrev_b32_e32 v11, 2, v11
	s_and_b32 s24, s13, 0x60
	s_add_i32 m0, s48, 0x18000
	v_lshl_add_u64 v[4:5], v[4:5], 0, s[28:29]
	v_lshl_add_u64 v[16:17], s[34:35], 0, v[160:161]
	v_mov_b32_e32 v159, v3
	v_lshl_or_b32 v188, s14, 6, v15
	v_lshl_or_b32 v15, v15, 6, v21
	s_lshl_b32 s14, s14, 13
	v_and_b32_e32 v11, 32, v11
	s_lshl_b32 s13, s24, 7
	s_waitcnt vmcnt(2)
	s_barrier
	global_load_lds_dwordx4 v[4:5], off
	v_lshl_add_u64 v[4:5], v[6:7], 0, s[28:29]
	s_add_i32 m0, s48, 0x1a000
	s_add_i32 s52, s48, 0x8000
	s_add_i32 s53, s48, 0xa000
	v_lshl_add_u64 v[18:19], s[34:35], 0, v[158:159]
	v_bitop3_b32 v21, v15, s14, v11 bitop3:0xde
	global_load_lds_dwordx4 v[4:5], off
	v_lshl_add_u64 v[4:5], v[16:17], 0, s[28:29]
	s_mov_b32 m0, s52
	s_add_u32 s14, s10, 0x80080
	global_load_lds_dwordx4 v[4:5], off
	v_lshl_add_u64 v[4:5], v[18:19], 0, s[28:29]
	s_mov_b32 m0, s53
	s_addc_u32 s15, s11, 0
	global_load_lds_dwordx4 v[4:5], off
	s_add_i32 m0, s48, 0x1c000
	v_lshl_add_u64 v[4:5], s[14:15], 0, v[2:3]
	global_load_lds_dwordx4 v[4:5], off
	v_lshl_add_u64 v[4:5], s[14:15], 0, v[156:157]
	s_add_i32 m0, s48, 0x1e000
	s_cmpk_lt_u32 s12, 0x100
	global_load_lds_dwordx4 v[4:5], off
	v_lshlrev_b32_e32 v4, 15, v13
	v_and_b32_e32 v4, 0xffff0000, v4
	v_lshl_add_u32 v4, v12, 12, v4
	v_and_b32_e32 v5, 1, v13
	v_lshl_or_b32 v4, v5, 6, v4
	v_lshl_add_u32 v162, v14, 1, v4
	v_lshlrev_b32_e32 v4, 15, v8
	v_and_b32_e32 v4, 0xffff0000, v4
	v_lshl_add_u32 v4, v9, 12, v4
	v_and_b32_e32 v5, 1, v8
	s_waitcnt vmcnt(6)
	v_lshl_or_b32 v4, v5, 6, v4
	v_lshl_add_u32 v168, v10, 1, v4
	v_mov_b32_e32 v4, 0
	v_readlane_b32 s14, v241, 22
	v_bitop3_b32 v189, v15, s13, v11 bitop3:0xde
	s_cselect_b64 s[12:13], -1, 0
	s_mov_b32 s56, 0
	v_cmp_eq_u32_e64 s[38:39], 0, v20
	v_lshl_or_b32 v190, v20, 3, s24
	v_mov_b32_e32 v163, v3
	v_mov_b32_e32 v169, v3
	v_add_u32_e32 v191, 0, v21
	v_readlane_b32 s54, v241, 17
	s_mov_b32 s55, s14
	s_nop 0
	s_barrier
	v_readlane_b32 s15, v241, 23
	s_branch .LBB0_859
.LBB0_858:
	v_mov_b32_e32 v4, 0
	s_mov_b32 s54, s14
	s_mov_b32 s55, s26
	s_nop 0
	s_mov_b64 s[34:35], s[44:45]
	s_mov_b32 s56, s57
	s_andn2_b64 vcc, exec, s[40:41]
	s_mov_b64 s[10:11], s[36:37]
	s_cbranch_vccz .LBB0_889

.LBB0_865:
	s_add_u32 s60, s10, 0x100
	s_addc_u32 s61, s11, 0
	s_add_i32 s26, s26, s89
	s_ashr_i32 s27, s26, 31
	s_lshl_b64 s[24:25], s[26:27], 20
	s_add_u32 s44, s64, s24
	s_addc_u32 s45, s65, s25
	s_and_b64 s[24:25], s[42:43], exec
	s_cselect_b32 s27, s45, s35
	s_cselect_b32 s62, s44, s34
	s_ashr_i32 s15, s14, 31
	s_lshl_b64 s[24:25], s[14:15], 20
	s_add_u32 s36, s46, s24
	s_addc_u32 s37, s20, s25
	s_and_b64 s[24:25], s[42:43], exec
	s_cselect_b32 s15, s37, s11
	s_cselect_b32 s63, s36, s10
	s_add_u32 s10, s34, 0x80080
	s_addc_u32 s11, s35, 0
	s_waitcnt lgkmcnt(0)
	v_lshl_add_u64 v[132:133], s[10:11], 0, v[162:163]
	v_lshl_add_u64 v[134:135], s[10:11], 0, v[168:169]
	s_mov_b32 s66, -2
	s_mov_b64 s[10:11], 0
	s_add_u32 s24, s34, s10
	s_addc_u32 s25, s35, s11
	s_add_u32 s24, s24, 0x100
	s_addc_u32 s25, s25, 0
	s_add_u32 s67, s60, s10
	s_addc_u32 s74, s61, s11
	s_add_i32 s75, 0, 0x10000
	s_cmpk_eq_i32 s10, 0xf00
	s_cselect_b32 s31, s27, s25
	s_cselect_b32 s30, s62, s24
	s_cselect_b32 s25, s15, s74
	s_cselect_b32 s24, s63, s67
	s_add_i32 s67, 0, 0x14000
	v_add_u32_e32 v148, s75, v189
	v_add_u32_e32 v178, s67, v189
	ds_read_b128 v[136:139], v148
	ds_read_b128 v[140:143], v148 offset:1024
	ds_read_b128 v[144:147], v148 offset:2048
	ds_read_b128 v[148:151], v148 offset:3072
	ds_read_b128 v[152:155], v178
	ds_read_b128 v[170:173], v178 offset:1024
	ds_read_b128 v[174:177], v178 offset:2048
	ds_read_b128 v[178:181], v178 offset:3072
	v_lshl_add_u64 v[186:187], v[132:133], 0, s[10:11]
	s_add_i32 m0, s48, 0xc000
	ds_read_b128 v[182:185], v191
	ds_read_b128 v[192:195], v191 offset:1024
	ds_read_b128 v[204:207], v191 offset:2048
	ds_read_b128 v[208:211], v191 offset:3072
	ds_read_b128 v[212:215], v191 offset:4096
	ds_read_b128 v[216:219], v191 offset:5120
	ds_read_b128 v[220:223], v191 offset:6144
	ds_read_b128 v[224:227], v191 offset:7168
	global_load_lds_dwordx4 v[186:187], off
	v_lshl_add_u64 v[186:187], v[134:135], 0, s[10:11]
	s_add_i32 m0, s48, 0xe000
	s_nop 0
	global_load_lds_dwordx4 v[186:187], off
	s_waitcnt vmcnt(8)
	s_waitcnt lgkmcnt(0)
	s_barrier
	s_setprio 1
	s_waitcnt lgkmcnt(0)
	v_mfma_f32_16x16x32_bf16 v[128:131], v[136:139], v[182:185], 0
	v_mfma_f32_16x16x32_bf16 v[124:127], v[144:147], v[182:185], 0
	v_mfma_f32_16x16x32_bf16 v[120:123], v[136:139], v[204:207], 0
	v_mfma_f32_16x16x32_bf16 v[116:119], v[144:147], v[204:207], 0
	v_mfma_f32_16x16x32_bf16 v[112:115], v[136:139], v[212:215], 0
	v_mfma_f32_16x16x32_bf16 v[108:111], v[144:147], v[212:215], 0
	v_mfma_f32_16x16x32_bf16 v[104:107], v[136:139], v[220:223], 0
	v_mfma_f32_16x16x32_bf16 v[100:103], v[144:147], v[220:223], 0
	v_mfma_f32_16x16x32_bf16 v[128:131], v[140:143], v[192:195], v[128:131]
	v_mfma_f32_16x16x32_bf16 v[124:127], v[148:151], v[192:195], v[124:127]
	v_mfma_f32_16x16x32_bf16 v[120:123], v[140:143], v[208:211], v[120:123]
	v_mfma_f32_16x16x32_bf16 v[116:119], v[148:151], v[208:211], v[116:119]
	v_mfma_f32_16x16x32_bf16 v[112:115], v[140:143], v[216:219], v[112:115]
	v_mfma_f32_16x16x32_bf16 v[108:111], v[148:151], v[216:219], v[108:111]
	v_mfma_f32_16x16x32_bf16 v[104:107], v[140:143], v[224:227], v[104:107]
	v_mfma_f32_16x16x32_bf16 v[100:103], v[148:151], v[224:227], v[100:103]
	s_setprio 0
	s_setprio 1
	v_mfma_f32_16x16x32_bf16 v[96:99], v[152:155], v[182:185], 0
	v_mfma_f32_16x16x32_bf16 v[92:95], v[174:177], v[182:185], 0
	v_mfma_f32_16x16x32_bf16 v[88:91], v[152:155], v[204:207], 0
	v_mfma_f32_16x16x32_bf16 v[84:87], v[174:177], v[204:207], 0
	v_mfma_f32_16x16x32_bf16 v[80:83], v[152:155], v[212:215], 0
	v_mfma_f32_16x16x32_bf16 v[76:79], v[174:177], v[212:215], 0
	v_mfma_f32_16x16x32_bf16 v[72:75], v[152:155], v[220:223], 0
	v_mfma_f32_16x16x32_bf16 v[68:71], v[174:177], v[220:223], 0
	v_mfma_f32_16x16x32_bf16 v[96:99], v[170:173], v[192:195], v[96:99]
	v_mfma_f32_16x16x32_bf16 v[92:95], v[178:181], v[192:195], v[92:95]
	v_mfma_f32_16x16x32_bf16 v[88:91], v[170:173], v[208:211], v[88:91]
	v_mfma_f32_16x16x32_bf16 v[84:87], v[178:181], v[208:211], v[84:87]
	v_mfma_f32_16x16x32_bf16 v[80:83], v[170:173], v[216:219], v[80:83]
	v_mfma_f32_16x16x32_bf16 v[76:79], v[178:181], v[216:219], v[76:79]
	v_mfma_f32_16x16x32_bf16 v[72:75], v[170:173], v[224:227], v[72:75]
	v_mfma_f32_16x16x32_bf16 v[68:71], v[178:181], v[224:227], v[68:71]
	s_setprio 0
	s_barrier
	s_add_i32 s74, s75, s47
	v_lshl_add_u64 v[186:187], s[24:25], 0, v[2:3]
	s_mov_b32 m0, s74
	ds_read_b128 v[182:185], v191 offset:16384
	ds_read_b128 v[192:195], v191 offset:17408
	ds_read_b128 v[204:207], v191 offset:18432
	ds_read_b128 v[208:211], v191 offset:19456
	ds_read_b128 v[212:215], v191 offset:20480
	ds_read_b128 v[216:219], v191 offset:21504
	ds_read_b128 v[220:223], v191 offset:22528
	ds_read_b128 v[224:227], v191 offset:23552
	global_load_lds_dwordx4 v[186:187], off
	s_add_i32 m0, s74, 0x2000
	s_add_u32 s74, s24, 0x80000
	v_lshl_add_u64 v[196:197], s[24:25], 0, v[156:157]
	s_addc_u32 s75, s25, 0
	s_add_i32 s67, s67, s47
	global_load_lds_dwordx4 v[196:197], off
	v_lshl_add_u64 v[228:229], s[74:75], 0, v[2:3]
	s_mov_b32 m0, s67
	v_lshl_add_u64 v[230:231], s[30:31], 0, v[158:159]
	global_load_lds_dwordx4 v[228:229], off
	v_lshl_add_u64 v[228:229], s[74:75], 0, v[156:157]
	s_add_i32 m0, s67, 0x2000
	s_nop 0
	global_load_lds_dwordx4 v[228:229], off
	v_lshl_add_u64 v[228:229], s[30:31], 0, v[160:161]
	s_mov_b32 m0, s48
	s_nop 0
	global_load_lds_dwordx4 v[228:229], off
	s_mov_b32 m0, s49
	s_nop 0
	global_load_lds_dwordx4 v[230:231], off
	s_waitcnt vmcnt(8)
	s_waitcnt lgkmcnt(0)
	s_barrier
	s_setprio 1
	s_waitcnt lgkmcnt(0)
	v_mfma_f32_16x16x32_bf16 v[64:67], v[136:139], v[182:185], 0
	v_mfma_f32_16x16x32_bf16 v[60:63], v[144:147], v[182:185], 0
	v_mfma_f32_16x16x32_bf16 v[56:59], v[136:139], v[204:207], 0
	v_mfma_f32_16x16x32_bf16 v[52:55], v[144:147], v[204:207], 0
	v_mfma_f32_16x16x32_bf16 v[48:51], v[136:139], v[212:215], 0
	v_mfma_f32_16x16x32_bf16 v[44:47], v[144:147], v[212:215], 0
	v_mfma_f32_16x16x32_bf16 v[40:43], v[136:139], v[220:223], 0
	v_mfma_f32_16x16x32_bf16 v[36:39], v[144:147], v[220:223], 0
	v_mfma_f32_16x16x32_bf16 v[64:67], v[140:143], v[192:195], v[64:67]
	v_mfma_f32_16x16x32_bf16 v[60:63], v[148:151], v[192:195], v[60:63]
	v_mfma_f32_16x16x32_bf16 v[56:59], v[140:143], v[208:211], v[56:59]
	v_mfma_f32_16x16x32_bf16 v[52:55], v[148:151], v[208:211], v[52:55]
	v_mfma_f32_16x16x32_bf16 v[48:51], v[140:143], v[216:219], v[48:51]
	v_mfma_f32_16x16x32_bf16 v[44:47], v[148:151], v[216:219], v[44:47]
	v_mfma_f32_16x16x32_bf16 v[40:43], v[140:143], v[224:227], v[40:43]
	v_mfma_f32_16x16x32_bf16 v[36:39], v[148:151], v[224:227], v[36:39]
	s_setprio 0
	s_setprio 1
	v_mfma_f32_16x16x32_bf16 v[32:35], v[152:155], v[182:185], 0
	v_mfma_f32_16x16x32_bf16 v[28:31], v[174:177], v[182:185], 0
	v_mfma_f32_16x16x32_bf16 v[24:27], v[152:155], v[204:207], 0
	v_mfma_f32_16x16x32_bf16 v[20:23], v[174:177], v[204:207], 0
	v_mfma_f32_16x16x32_bf16 v[16:19], v[152:155], v[212:215], 0
	v_mfma_f32_16x16x32_bf16 v[12:15], v[174:177], v[212:215], 0
	v_mfma_f32_16x16x32_bf16 v[8:11], v[152:155], v[220:223], 0
	v_mfma_f32_16x16x32_bf16 v[4:7], v[174:177], v[220:223], 0
	v_mfma_f32_16x16x32_bf16 v[32:35], v[170:173], v[192:195], v[32:35]
	v_mfma_f32_16x16x32_bf16 v[28:31], v[178:181], v[192:195], v[28:31]
	v_mfma_f32_16x16x32_bf16 v[24:27], v[170:173], v[208:211], v[24:27]
	v_mfma_f32_16x16x32_bf16 v[20:23], v[178:181], v[208:211], v[20:23]
	v_mfma_f32_16x16x32_bf16 v[16:19], v[170:173], v[216:219], v[16:19]
	v_mfma_f32_16x16x32_bf16 v[12:15], v[178:181], v[216:219], v[12:15]
	v_mfma_f32_16x16x32_bf16 v[8:11], v[170:173], v[224:227], v[8:11]
	v_mfma_f32_16x16x32_bf16 v[4:7], v[178:181], v[224:227], v[4:7]
	s_setprio 0
	s_barrier
	s_add_i32 s67, 0, 0x18000
	s_add_i32 s74, 0, 0x1c000
	v_add_u32_e32 v148, s67, v189
	v_add_u32_e32 v178, s74, v189
	ds_read_b128 v[136:139], v148
	ds_read_b128 v[140:143], v148 offset:1024
	ds_read_b128 v[144:147], v148 offset:2048
	ds_read_b128 v[148:151], v148 offset:3072
	ds_read_b128 v[152:155], v178
	ds_read_b128 v[170:173], v178 offset:1024
	ds_read_b128 v[174:177], v178 offset:2048
	ds_read_b128 v[178:181], v178 offset:3072
	s_add_u32 s30, s30, 0x80000
	s_addc_u32 s31, s31, 0
	s_mov_b32 m0, s50
	v_lshl_add_u64 v[232:233], s[30:31], 0, v[160:161]
	ds_read_b128 v[182:185], v191 offset:32768
	ds_read_b128 v[192:195], v191 offset:33792
	ds_read_b128 v[204:207], v191 offset:34816
	ds_read_b128 v[208:211], v191 offset:35840
	ds_read_b128 v[212:215], v191 offset:36864
	ds_read_b128 v[216:219], v191 offset:37888
	ds_read_b128 v[220:223], v191 offset:38912
	ds_read_b128 v[224:227], v191 offset:39936
	global_load_lds_dwordx4 v[232:233], off
	v_lshl_add_u64 v[232:233], s[30:31], 0, v[158:159]
	s_mov_b32 m0, s51
	s_nop 0
	global_load_lds_dwordx4 v[232:233], off
	s_waitcnt vmcnt(8)
	s_waitcnt lgkmcnt(0)
	s_barrier
	s_setprio 1
	s_waitcnt lgkmcnt(0)
	v_mfma_f32_16x16x32_bf16 v[128:131], v[136:139], v[182:185], v[128:131]
	v_mfma_f32_16x16x32_bf16 v[124:127], v[144:147], v[182:185], v[124:127]
	v_mfma_f32_16x16x32_bf16 v[120:123], v[136:139], v[204:207], v[120:123]
	v_mfma_f32_16x16x32_bf16 v[116:119], v[144:147], v[204:207], v[116:119]
	v_mfma_f32_16x16x32_bf16 v[112:115], v[136:139], v[212:215], v[112:115]
	v_mfma_f32_16x16x32_bf16 v[108:111], v[144:147], v[212:215], v[108:111]
	v_mfma_f32_16x16x32_bf16 v[104:107], v[136:139], v[220:223], v[104:107]
	v_mfma_f32_16x16x32_bf16 v[100:103], v[144:147], v[220:223], v[100:103]
	v_mfma_f32_16x16x32_bf16 v[128:131], v[140:143], v[192:195], v[128:131]
	v_mfma_f32_16x16x32_bf16 v[124:127], v[148:151], v[192:195], v[124:127]
	v_mfma_f32_16x16x32_bf16 v[120:123], v[140:143], v[208:211], v[120:123]
	v_mfma_f32_16x16x32_bf16 v[116:119], v[148:151], v[208:211], v[116:119]
	v_mfma_f32_16x16x32_bf16 v[112:115], v[140:143], v[216:219], v[112:115]
	v_mfma_f32_16x16x32_bf16 v[108:111], v[148:151], v[216:219], v[108:111]
	v_mfma_f32_16x16x32_bf16 v[104:107], v[140:143], v[224:227], v[104:107]
	v_mfma_f32_16x16x32_bf16 v[100:103], v[148:151], v[224:227], v[100:103]
	s_setprio 0
	s_setprio 1
	v_mfma_f32_16x16x32_bf16 v[96:99], v[152:155], v[182:185], v[96:99]
	v_mfma_f32_16x16x32_bf16 v[92:95], v[174:177], v[182:185], v[92:95]
	v_mfma_f32_16x16x32_bf16 v[88:91], v[152:155], v[204:207], v[88:91]
	v_mfma_f32_16x16x32_bf16 v[84:87], v[174:177], v[204:207], v[84:87]
	v_mfma_f32_16x16x32_bf16 v[80:83], v[152:155], v[212:215], v[80:83]
	v_mfma_f32_16x16x32_bf16 v[76:79], v[174:177], v[212:215], v[76:79]
	v_mfma_f32_16x16x32_bf16 v[72:75], v[152:155], v[220:223], v[72:75]
	v_mfma_f32_16x16x32_bf16 v[68:71], v[174:177], v[220:223], v[68:71]
	v_mfma_f32_16x16x32_bf16 v[96:99], v[170:173], v[192:195], v[96:99]
	v_mfma_f32_16x16x32_bf16 v[92:95], v[178:181], v[192:195], v[92:95]
	v_mfma_f32_16x16x32_bf16 v[88:91], v[170:173], v[208:211], v[88:91]
	v_mfma_f32_16x16x32_bf16 v[84:87], v[178:181], v[208:211], v[84:87]
	v_mfma_f32_16x16x32_bf16 v[80:83], v[170:173], v[216:219], v[80:83]
	v_mfma_f32_16x16x32_bf16 v[76:79], v[178:181], v[216:219], v[76:79]
	v_mfma_f32_16x16x32_bf16 v[72:75], v[170:173], v[224:227], v[72:75]
	v_mfma_f32_16x16x32_bf16 v[68:71], v[178:181], v[224:227], v[68:71]
	s_setprio 0
	s_barrier
	s_add_i32 s30, s67, s47
	v_lshl_add_u64 v[186:187], v[186:187], 0, s[28:29]
	s_mov_b32 m0, s30
	ds_read_b128 v[182:185], v191 offset:49152
	ds_read_b128 v[192:195], v191 offset:50176
	ds_read_b128 v[204:207], v191 offset:51200
	ds_read_b128 v[208:211], v191 offset:52224
	ds_read_b128 v[212:215], v191 offset:53248
	ds_read_b128 v[216:219], v191 offset:54272
	ds_read_b128 v[220:223], v191 offset:55296
	ds_read_b128 v[224:227], v191 offset:56320
	global_load_lds_dwordx4 v[186:187], off
	s_add_i32 m0, s30, 0x2000
	s_add_u32 s24, s24, 0x80080
	v_lshl_add_u64 v[186:187], v[196:197], 0, s[28:29]
	s_addc_u32 s25, s25, 0
	s_add_i32 s30, s74, s47
	global_load_lds_dwordx4 v[186:187], off
	v_lshl_add_u64 v[186:187], s[24:25], 0, v[2:3]
	s_mov_b32 m0, s30
	s_nop 0
	global_load_lds_dwordx4 v[186:187], off
	v_lshl_add_u64 v[186:187], s[24:25], 0, v[156:157]
	s_add_i32 m0, s30, 0x2000
	s_nop 0
	global_load_lds_dwordx4 v[186:187], off
	v_lshl_add_u64 v[186:187], v[228:229], 0, s[28:29]
	s_mov_b32 m0, s52
	s_nop 0
	global_load_lds_dwordx4 v[186:187], off
	v_lshl_add_u64 v[186:187], v[230:231], 0, s[28:29]
	s_mov_b32 m0, s53
	s_nop 0
	global_load_lds_dwordx4 v[186:187], off
	s_waitcnt vmcnt(8)
	s_waitcnt lgkmcnt(0)
	s_barrier
	s_setprio 1
	s_waitcnt lgkmcnt(0)
	v_mfma_f32_16x16x32_bf16 v[64:67], v[136:139], v[182:185], v[64:67]
	v_mfma_f32_16x16x32_bf16 v[60:63], v[144:147], v[182:185], v[60:63]
	v_mfma_f32_16x16x32_bf16 v[56:59], v[136:139], v[204:207], v[56:59]
	v_mfma_f32_16x16x32_bf16 v[52:55], v[144:147], v[204:207], v[52:55]
	v_mfma_f32_16x16x32_bf16 v[48:51], v[136:139], v[212:215], v[48:51]
	v_mfma_f32_16x16x32_bf16 v[44:47], v[144:147], v[212:215], v[44:47]
	v_mfma_f32_16x16x32_bf16 v[40:43], v[136:139], v[220:223], v[40:43]
	v_mfma_f32_16x16x32_bf16 v[36:39], v[144:147], v[220:223], v[36:39]
	v_mfma_f32_16x16x32_bf16 v[64:67], v[140:143], v[192:195], v[64:67]
	v_mfma_f32_16x16x32_bf16 v[60:63], v[148:151], v[192:195], v[60:63]
	v_mfma_f32_16x16x32_bf16 v[56:59], v[140:143], v[208:211], v[56:59]
	v_mfma_f32_16x16x32_bf16 v[52:55], v[148:151], v[208:211], v[52:55]
	v_mfma_f32_16x16x32_bf16 v[48:51], v[140:143], v[216:219], v[48:51]
	v_mfma_f32_16x16x32_bf16 v[44:47], v[148:151], v[216:219], v[44:47]
	v_mfma_f32_16x16x32_bf16 v[40:43], v[140:143], v[224:227], v[40:43]
	v_mfma_f32_16x16x32_bf16 v[36:39], v[148:151], v[224:227], v[36:39]
	s_setprio 0
	s_setprio 1
	v_mfma_f32_16x16x32_bf16 v[32:35], v[152:155], v[182:185], v[32:35]
	v_mfma_f32_16x16x32_bf16 v[28:31], v[174:177], v[182:185], v[28:31]
	v_mfma_f32_16x16x32_bf16 v[24:27], v[152:155], v[204:207], v[24:27]
	v_mfma_f32_16x16x32_bf16 v[20:23], v[174:177], v[204:207], v[20:23]
	v_mfma_f32_16x16x32_bf16 v[16:19], v[152:155], v[212:215], v[16:19]
	v_mfma_f32_16x16x32_bf16 v[12:15], v[174:177], v[212:215], v[12:15]
	v_mfma_f32_16x16x32_bf16 v[8:11], v[152:155], v[220:223], v[8:11]
	v_mfma_f32_16x16x32_bf16 v[4:7], v[174:177], v[220:223], v[4:7]
	v_mfma_f32_16x16x32_bf16 v[32:35], v[170:173], v[192:195], v[32:35]
	v_mfma_f32_16x16x32_bf16 v[28:31], v[178:181], v[192:195], v[28:31]
	v_mfma_f32_16x16x32_bf16 v[24:27], v[170:173], v[208:211], v[24:27]
	v_mfma_f32_16x16x32_bf16 v[20:23], v[178:181], v[208:211], v[20:23]
	v_mfma_f32_16x16x32_bf16 v[16:19], v[170:173], v[216:219], v[16:19]
	v_mfma_f32_16x16x32_bf16 v[12:15], v[178:181], v[216:219], v[12:15]
	v_mfma_f32_16x16x32_bf16 v[8:11], v[170:173], v[224:227], v[8:11]
	v_mfma_f32_16x16x32_bf16 v[4:7], v[178:181], v[224:227], v[4:7]
	s_setprio 0
	s_barrier
	s_add_i32 s66, s66, 2
	s_add_u32 s10, s10, 0x100
	s_addc_u32 s11, s11, 0
